# in-proj epilogue result stores made write-through (sc1) to shorten the release fence at the next grid barrier
# baseline (speedup 1.0000x reference)
; DEVI float sigmoidf_(float x) { return __builtin_amdgcn_rcpf(1.0f + __expf(-x)); }
;     DEVI void operator()(const f32x4 (&acc)[2][2][4][2], const Unit& u, int wr, int wc, int fr, int fq) const {
;     ...
;         if (plain) {
;             bf16_t* base; int ld, pnl; bool sg = false;
;             if (pn < 32) { base = G; ld = 8192; pnl = pn; sg = true; }
;             else if (pn < 39) { base = P1G; ld = 1792; pnl = pn - 32; }
;             else { base = P1R; ld = 2048; pnl = pn - 48; }
; #pragma unroll
;             for (int ai = 0; ai < 2; ++ai)
; #pragma unroll
;                 for (int m = 0; m < 4; ++m) {
;                     bf16_t* rowp = base + (size_t)(row0 + ai * 128 + m * 16) * ld + pnl * 256 + cl;
; #pragma unroll
;                     for (int bj = 0; bj < 2; ++bj) {
;                         f32x4 v0 = acc[ai][bj][m][0], v1 = acc[ai][bj][m][1];
;                         if (sg) {
; #pragma unroll
;                             for (int j = 0; j < 4; ++j) { v0[j] = sigmoidf_(v0[j]); v1[j] = sigmoidf_(v1[j]); }
;                         }
;                         u32x4 w; w.x = cvt_pk_bf16(v0[0], v0[1]); w.y = cvt_pk_bf16(v0[2], v0[3]); w.z = cvt_pk_bf16(v1[0], v1[1]); w.w = cvt_pk_bf16(v1[2], v1[3]);
;                         *(u32x4*)(rowp + bj * 128) = w;
;                     }
.LBB0_207:
	v_cvt_pk_bf16_f32 v4, v4, v5
	v_cvt_pk_bf16_f32 v5, v6, v7
	v_cvt_pk_bf16_f32 v6, v0, v1
	v_cvt_pk_bf16_f32 v7, v2, v3
	global_store_dwordx4 v[16:17], v[4:7], off offset:256 sc1

;     DEVI void operator()(const f32x4 (&acc)[2][2][4][2], const Unit& u, int wr, int wc, int fr, int fq) const {
;     ...
;             int t, hbase, arr0;
;             if (pn < 48) { const int pl = pn - 39; t = pl / 3; hbase = (pl % 3) * 2; arr0 = t * 6 + hbase; }
;             else { const int pl = pn - 56; t = pl / 2; hbase = (pl % 2) * 2; arr0 = 18 + t * 4 + hbase; }
;             const bool rope = (t < 2) && (wc == 0);
;             const float sc = (t == 0) ? 0.08838834764831845f : 1.0f;
; #pragma unroll
;             for (int ai = 0; ai < 2; ++ai)
; #pragma unroll
;                 for (int m = 0; m < 4; ++m) {
;                     const int row = row0 + ai * 128 + m * 16;
; #pragma unroll
;                     for (int bj = 0; bj < 2; ++bj) {
;                         f32x4 v0 = acc[ai][bj][m][0], v1 = acc[ai][bj][m][1];
;                         if (rope) {
;                             const f32x4 c0 = *(const f32x4*)(cosT + (size_t)row * 16 + 8 * (fq & 1)), c1 = *(const f32x4*)(cosT + (size_t)row * 16 + 8 * (fq & 1) + 4);
;                             const f32x4 s0 = *(const f32x4*)(sinT + (size_t)row * 16 + 8 * (fq & 1)), s1 = *(const f32x4*)(sinT + (size_t)row * 16 + 8 * (fq & 1) + 4);
;                             const float sgn = (fq < 2) ? -1.0f : 1.0f;
; #pragma unroll
;                             for (int j = 0; j < 4; ++j) {
;                                 const float p0 = __shfl_xor(v0[j], 32), p1 = __shfl_xor(v1[j], 32);
;                                 v0[j] = v0[j] * c0[j] + sgn * p0 * s0[j];
;                                 v1[j] = v1[j] * c1[j] + sgn * p1 * s1[j];
;                             }
;                         }
;                         v0 *= sc; v1 *= sc;
;                         bf16_t* dst = P2 + (size_t)(arr0 + bj) * ((size_t)S * 128) + (size_t)row * 128 + cl;
;                         u32x4 w; w.x = cvt_pk_bf16(v0[0], v0[1]); w.y = cvt_pk_bf16(v0[2], v0[3]); w.z = cvt_pk_bf16(v1[0], v1[1]); w.w = cvt_pk_bf16(v1[2], v1[3]);
;                         *(u32x4*)dst = w;
.LBB0_225:
	s_cmp_eq_u32 s2, 0
	s_cselect_b64 vcc, -1, 0
	s_lshl_b64 s[0:1], s[72:73], 22
	v_readlane_b32 s2, v254, 18
	v_mov_b32_e32 v148, 0x3db504f3
	s_add_u32 s24, s2, s0
	v_readlane_b32 s0, v254, 19
	v_cndmask_b32_e32 v170, 1.0, v148, vcc
	v_lshlrev_b64 v[174:175], 8, v[168:169]
	s_addc_u32 s25, s0, s1
	v_pk_mul_f32 v[130:131], v[170:171], v[130:131] op_sel_hi:[0,1]
	v_pk_mul_f32 v[128:129], v[170:171], v[128:129] op_sel_hi:[0,1]
	v_pk_mul_f32 v[134:135], v[170:171], v[134:135] op_sel_hi:[0,1]
	v_pk_mul_f32 v[132:133], v[170:171], v[132:133] op_sel_hi:[0,1]
	v_lshl_add_u64 v[178:179], s[24:25], 0, v[174:175]
	v_lshlrev_b32_e32 v148, 1, v144
	v_lshl_add_u64 v[178:179], v[178:179], 0, v[148:149]
	v_cvt_pk_bf16_f32 v128, v128, v129
	v_cvt_pk_bf16_f32 v129, v130, v131
	v_cvt_pk_bf16_f32 v130, v132, v133
	v_cvt_pk_bf16_f32 v131, v134, v135
	global_store_dwordx4 v[178:179], v[128:131], off sc1
	v_mov_b64_e32 v[134:135], v[114:115]
	s_and_b64 vcc, exec, s[8:9]
	v_mov_b64_e32 v[130:131], v[118:119]
	v_mov_b64_e32 v[128:129], v[116:117]
	v_mov_b64_e32 v[132:133], v[112:113]
	s_cbranch_vccnz .LBB0_227
	global_load_dwordx4 v[130:133], v[176:177], off offset:16
	s_nop 0
	global_load_dwordx4 v[176:179], v[176:177], off
	s_nop 0
	global_load_dwordx4 v[182:185], v[172:173], off offset:16
	global_load_dwordx4 v[186:189], v[172:173], off
	v_cmp_lt_i32_e32 vcc, v209, v203
	s_waitcnt vmcnt(0)
	v_mul_f32_e32 v190, v114, v132
	v_cndmask_b32_e32 v128, v202, v209, vcc
	v_lshlrev_b32_e32 v156, 2, v128
	v_pk_mul_f32 v[172:173], v[116:117], v[176:177]
	v_pk_mul_f32 v[176:177], v[112:113], v[130:131]
	ds_bpermute_b32 v131, v156, v118
	ds_bpermute_b32 v157, v156, v114
	ds_bpermute_b32 v128, v156, v116
	ds_bpermute_b32 v129, v156, v117
	v_mul_f32_e32 v130, v118, v178
	s_waitcnt lgkmcnt(0)
	v_mul_f32_e32 v131, v146, v131
	v_mul_f32_e32 v178, v188, v131
	v_mul_f32_e32 v131, v146, v157
	v_mul_f32_e32 v192, v184, v131
	ds_bpermute_b32 v131, v156, v119
	ds_bpermute_b32 v132, v156, v115
	ds_bpermute_b32 v134, v156, v112
	ds_bpermute_b32 v135, v156, v113
	v_pk_mul_f32 v[128:129], v[146:147], v[128:129]
	s_waitcnt lgkmcnt(3)
	v_mul_f32_e32 v195, v146, v131
	v_mov_b32_e32 v188, v119
	v_mov_b32_e32 v194, v179
	v_pk_fma_f32 v[128:129], v[186:187], v[128:129], v[172:173]
	s_waitcnt lgkmcnt(2)
	v_mul_f32_e32 v173, v146, v132
	v_mov_b32_e32 v184, v115
	v_mov_b32_e32 v172, v133
	v_pk_mul_f32 v[188:189], v[188:189], v[194:195]
	v_pk_mul_f32 v[132:133], v[184:185], v[172:173]
	s_waitcnt lgkmcnt(0)
	v_pk_mul_f32 v[134:135], v[146:147], v[134:135]
	v_mov_b32_e32 v131, v188
	v_mov_b32_e32 v179, v189
	v_mov_b32_e32 v191, v132
	v_mov_b32_e32 v193, v133
	v_pk_add_f32 v[130:131], v[130:131], v[178:179]
	v_pk_fma_f32 v[132:133], v[182:183], v[134:135], v[176:177]
	v_pk_add_f32 v[134:135], v[190:191], v[192:193]
.LBB0_227:
	s_add_i32 s72, s72, 1
	s_lshl_b64 s[0:1], s[72:73], 22
	v_readlane_b32 s2, v254, 18
	s_add_u32 s26, s2, s0
	v_readlane_b32 s0, v254, 19
	v_mov_b32_e32 v171, v170
	v_mov_b32_e32 v172, v170
	v_mov_b32_e32 v173, v170
	s_addc_u32 s27, s0, s1
	v_pk_mul_f32 v[130:131], v[172:173], v[130:131]
	v_pk_mul_f32 v[128:129], v[170:171], v[128:129]
	v_pk_mul_f32 v[134:135], v[172:173], v[134:135]
	v_pk_mul_f32 v[132:133], v[170:171], v[132:133]
	v_lshl_add_u64 v[174:175], s[26:27], 0, v[174:175]
	v_lshl_add_u64 v[174:175], v[174:175], 0, v[148:149]
	v_cvt_pk_bf16_f32 v128, v128, v129
	v_cvt_pk_bf16_f32 v129, v130, v131
	v_cvt_pk_bf16_f32 v130, v132, v133
	v_cvt_pk_bf16_f32 v131, v134, v135
	global_store_dwordx4 v[174:175], v[128:131], off sc1
	v_or_b32_e32 v178, 16, v168
	v_ashrrev_i32_e32 v179, 31, v178
	v_lshlrev_b64 v[128:129], 4, v[178:179]
	v_lshlrev_b64 v[128:129], 2, v[128:129]
	v_lshl_add_u64 v[176:177], v[160:161], 0, v[128:129]
	v_lshl_add_u64 v[174:175], v[162:163], 0, v[128:129]
	v_mov_b64_e32 v[130:131], v[110:111]
	v_mov_b64_e32 v[134:135], v[106:107]
	s_and_b64 vcc, exec, s[8:9]
	v_mov_b64_e32 v[128:129], v[108:109]
	v_mov_b64_e32 v[132:133], v[104:105]
	s_cbranch_vccnz .LBB0_229
	global_load_dwordx4 v[130:133], v[176:177], off offset:16
	global_load_dwordx4 v[182:185], v[176:177], off
	global_load_dwordx4 v[186:189], v[174:175], off offset:16
	global_load_dwordx4 v[190:193], v[174:175], off
	v_cmp_lt_i32_e32 vcc, v209, v203
	s_waitcnt vmcnt(0)
	v_pk_mul_f32 v[194:195], v[104:105], v[130:131]
	v_cndmask_b32_e32 v128, v202, v209, vcc
	v_lshlrev_b32_e32 v156, 2, v128
	ds_bpermute_b32 v131, v156, v110
	ds_bpermute_b32 v157, v156, v106
	ds_bpermute_b32 v128, v156, v108
	ds_bpermute_b32 v129, v156, v109
	v_mul_f32_e32 v130, v110, v184
	s_waitcnt lgkmcnt(0)
	v_mul_f32_e32 v131, v146, v131
	v_mul_f32_e32 v184, v192, v131
	v_mul_f32_e32 v131, v146, v157
	v_mul_f32_e32 v196, v106, v132
	v_mul_f32_e32 v218, v188, v131
	ds_bpermute_b32 v131, v156, v111
	ds_bpermute_b32 v132, v156, v107
	ds_bpermute_b32 v134, v156, v104
	ds_bpermute_b32 v135, v156, v105
	v_pk_mul_f32 v[182:183], v[108:109], v[182:183]
	v_pk_mul_f32 v[128:129], v[146:147], v[128:129]
	s_waitcnt lgkmcnt(3)
	v_mul_f32_e32 v221, v146, v131
	v_mov_b32_e32 v192, v111
	v_mov_b32_e32 v220, v185
	v_pk_fma_f32 v[128:129], v[190:191], v[128:129], v[182:183]
	s_waitcnt lgkmcnt(2)
	v_mul_f32_e32 v183, v146, v132
	v_mov_b32_e32 v188, v107
	v_mov_b32_e32 v182, v133
	v_pk_mul_f32 v[192:193], v[192:193], v[220:221]
	v_pk_mul_f32 v[132:133], v[188:189], v[182:183]
	s_waitcnt lgkmcnt(0)
	v_pk_mul_f32 v[134:135], v[146:147], v[134:135]
	v_mov_b32_e32 v131, v192
	v_mov_b32_e32 v185, v193
	v_mov_b32_e32 v197, v132
	v_mov_b32_e32 v219, v133
	v_pk_add_f32 v[130:131], v[130:131], v[184:185]
	v_pk_fma_f32 v[132:133], v[186:187], v[134:135], v[194:195]
	v_pk_add_f32 v[134:135], v[196:197], v[218:219]
;     DEVI void operator()(const f32x4 (&acc)[2][2][4][2], const Unit& u, int wr, int wc, int fr, int fq) const {
;     ...
;                 for (int m = 0; m < 4; ++m) {
;                     const int row = row0 + ai * 128 + m * 16;
; #pragma unroll
;                     for (int bj = 0; bj < 2; ++bj) {
;                         f32x4 v0 = acc[ai][bj][m][0], v1 = acc[ai][bj][m][1];
;                         if (rope) {
;                             const f32x4 c0 = *(const f32x4*)(cosT + (size_t)row * 16 + 8 * (fq & 1)), c1 = *(const f32x4*)(cosT + (size_t)row * 16 + 8 * (fq & 1) + 4);
;                             const f32x4 s0 = *(const f32x4*)(sinT + (size_t)row * 16 + 8 * (fq & 1)), s1 = *(const f32x4*)(sinT + (size_t)row * 16 + 8 * (fq & 1) + 4);
;                             const float sgn = (fq < 2) ? -1.0f : 1.0f;
; #pragma unroll
;                             for (int j = 0; j < 4; ++j) {
;                                 const float p0 = __shfl_xor(v0[j], 32), p1 = __shfl_xor(v1[j], 32);
;                                 v0[j] = v0[j] * c0[j] + sgn * p0 * s0[j];
;                                 v1[j] = v1[j] * c1[j] + sgn * p1 * s1[j];
;                             }
;                         }
;                         v0 *= sc; v1 *= sc;
;                         bf16_t* dst = P2 + (size_t)(arr0 + bj) * ((size_t)S * 128) + (size_t)row * 128 + cl;
;                         u32x4 w; w.x = cvt_pk_bf16(v0[0], v0[1]); w.y = cvt_pk_bf16(v0[2], v0[3]); w.z = cvt_pk_bf16(v1[0], v1[1]); w.w = cvt_pk_bf16(v1[2], v1[3]);
;                         *(u32x4*)dst = w;
.LBB0_229:
	v_lshlrev_b64 v[178:179], 8, v[178:179]
	v_pk_mul_f32 v[130:131], v[172:173], v[130:131]
	v_pk_mul_f32 v[128:129], v[170:171], v[128:129]
	v_pk_mul_f32 v[134:135], v[172:173], v[134:135]
	v_pk_mul_f32 v[132:133], v[170:171], v[132:133]
	v_lshl_add_u64 v[172:173], s[24:25], 0, v[178:179]
	v_lshl_add_u64 v[172:173], v[172:173], 0, v[148:149]
	v_cvt_pk_bf16_f32 v128, v128, v129
	v_cvt_pk_bf16_f32 v129, v130, v131
	v_cvt_pk_bf16_f32 v130, v132, v133
	v_cvt_pk_bf16_f32 v131, v134, v135
	global_store_dwordx4 v[172:173], v[128:131], off sc1
	v_mov_b64_e32 v[134:135], v[98:99]
	s_and_b64 vcc, exec, s[8:9]
	v_mov_b64_e32 v[130:131], v[102:103]
	v_mov_b64_e32 v[128:129], v[100:101]
	v_mov_b64_e32 v[132:133], v[96:97]
	s_cbranch_vccnz .LBB0_231
	global_load_dwordx4 v[130:133], v[176:177], off offset:16
	global_load_dwordx4 v[182:185], v[176:177], off
	global_load_dwordx4 v[186:189], v[174:175], off offset:16
	s_nop 0
	global_load_dwordx4 v[172:175], v[174:175], off
	v_cmp_lt_i32_e32 vcc, v209, v203
	s_waitcnt vmcnt(0)
	v_mul_f32_e32 v190, v98, v132
	v_cndmask_b32_e32 v128, v202, v209, vcc
	v_lshlrev_b32_e32 v156, 2, v128
	v_pk_mul_f32 v[176:177], v[100:101], v[182:183]
	v_pk_mul_f32 v[182:183], v[96:97], v[130:131]
	ds_bpermute_b32 v131, v156, v102
	ds_bpermute_b32 v157, v156, v98
	ds_bpermute_b32 v128, v156, v100
	ds_bpermute_b32 v129, v156, v101
	v_mul_f32_e32 v130, v102, v184
	s_waitcnt lgkmcnt(0)
	v_mul_f32_e32 v131, v146, v131
	v_mul_f32_e32 v184, v174, v131
	v_mul_f32_e32 v131, v146, v157
	v_mul_f32_e32 v192, v188, v131
	ds_bpermute_b32 v131, v156, v103
	ds_bpermute_b32 v132, v156, v99
	ds_bpermute_b32 v134, v156, v96
	ds_bpermute_b32 v135, v156, v97
	v_pk_mul_f32 v[128:129], v[146:147], v[128:129]
	s_waitcnt lgkmcnt(3)
	v_mul_f32_e32 v195, v146, v131
	v_mov_b32_e32 v174, v103
	v_mov_b32_e32 v194, v185
	v_pk_fma_f32 v[128:129], v[172:173], v[128:129], v[176:177]
	s_waitcnt lgkmcnt(2)
	v_mul_f32_e32 v173, v146, v132
	v_mov_b32_e32 v188, v99
	v_mov_b32_e32 v172, v133
	v_pk_mul_f32 v[174:175], v[174:175], v[194:195]
	v_pk_mul_f32 v[132:133], v[188:189], v[172:173]
	s_waitcnt lgkmcnt(0)
	v_pk_mul_f32 v[134:135], v[146:147], v[134:135]
	v_mov_b32_e32 v131, v174
	v_mov_b32_e32 v185, v175
	v_mov_b32_e32 v191, v132
	v_mov_b32_e32 v193, v133
	v_pk_add_f32 v[130:131], v[130:131], v[184:185]
	v_pk_fma_f32 v[132:133], v[186:187], v[134:135], v[182:183]
	v_pk_add_f32 v[134:135], v[190:191], v[192:193]
.LBB0_231:
	v_mov_b32_e32 v174, v170
	v_mov_b32_e32 v175, v170
	v_pk_mul_f32 v[130:131], v[174:175], v[130:131]
	v_pk_mul_f32 v[128:129], v[170:171], v[128:129]
	v_pk_mul_f32 v[134:135], v[174:175], v[134:135]
	v_pk_mul_f32 v[132:133], v[170:171], v[132:133]
	v_lshl_add_u64 v[172:173], s[26:27], 0, v[178:179]
	v_lshl_add_u64 v[172:173], v[172:173], 0, v[148:149]
	v_cvt_pk_bf16_f32 v128, v128, v129
	v_cvt_pk_bf16_f32 v129, v130, v131
	v_cvt_pk_bf16_f32 v130, v132, v133
	v_cvt_pk_bf16_f32 v131, v134, v135
	global_store_dwordx4 v[172:173], v[128:131], off sc1
	v_or_b32_e32 v178, 32, v168
	v_ashrrev_i32_e32 v179, 31, v178
	v_lshlrev_b64 v[128:129], 4, v[178:179]
	v_lshlrev_b64 v[128:129], 2, v[128:129]
	v_lshl_add_u64 v[176:177], v[160:161], 0, v[128:129]
	v_lshl_add_u64 v[172:173], v[162:163], 0, v[128:129]
	v_mov_b64_e32 v[130:131], v[94:95]
	v_mov_b64_e32 v[134:135], v[90:91]
	s_and_b64 vcc, exec, s[8:9]
	v_mov_b64_e32 v[128:129], v[92:93]
	v_mov_b64_e32 v[132:133], v[88:89]
	s_cbranch_vccnz .LBB0_233
	global_load_dwordx4 v[130:133], v[176:177], off offset:16
	global_load_dwordx4 v[182:185], v[176:177], off
	global_load_dwordx4 v[186:189], v[172:173], off offset:16
	global_load_dwordx4 v[190:193], v[172:173], off
	v_cmp_lt_i32_e32 vcc, v209, v203
	s_waitcnt vmcnt(0)
	v_pk_mul_f32 v[194:195], v[88:89], v[130:131]
	v_cndmask_b32_e32 v128, v202, v209, vcc
	v_lshlrev_b32_e32 v156, 2, v128
	ds_bpermute_b32 v131, v156, v94
	ds_bpermute_b32 v157, v156, v90
	ds_bpermute_b32 v128, v156, v92
	ds_bpermute_b32 v129, v156, v93
	v_mul_f32_e32 v130, v94, v184
	s_waitcnt lgkmcnt(0)
	v_mul_f32_e32 v131, v146, v131
	v_mul_f32_e32 v184, v192, v131
	v_mul_f32_e32 v131, v146, v157
	v_mul_f32_e32 v196, v90, v132
	v_mul_f32_e32 v218, v188, v131
	ds_bpermute_b32 v131, v156, v95
	ds_bpermute_b32 v132, v156, v91
	ds_bpermute_b32 v134, v156, v88
	ds_bpermute_b32 v135, v156, v89
	v_pk_mul_f32 v[182:183], v[92:93], v[182:183]
	v_pk_mul_f32 v[128:129], v[146:147], v[128:129]
	s_waitcnt lgkmcnt(3)
	v_mul_f32_e32 v221, v146, v131
	v_mov_b32_e32 v192, v95
	v_mov_b32_e32 v220, v185
	v_pk_fma_f32 v[128:129], v[190:191], v[128:129], v[182:183]
	s_waitcnt lgkmcnt(2)
	v_mul_f32_e32 v183, v146, v132
	v_mov_b32_e32 v188, v91
	v_mov_b32_e32 v182, v133
	v_pk_mul_f32 v[192:193], v[192:193], v[220:221]
	v_pk_mul_f32 v[132:133], v[188:189], v[182:183]
	s_waitcnt lgkmcnt(0)
	v_pk_mul_f32 v[134:135], v[146:147], v[134:135]
	v_mov_b32_e32 v131, v192
	v_mov_b32_e32 v185, v193
	v_mov_b32_e32 v197, v132
	v_mov_b32_e32 v219, v133
	v_pk_add_f32 v[130:131], v[130:131], v[184:185]
	v_pk_fma_f32 v[132:133], v[186:187], v[134:135], v[194:195]
	v_pk_add_f32 v[134:135], v[196:197], v[218:219]
;     DEVI void operator()(const f32x4 (&acc)[2][2][4][2], const Unit& u, int wr, int wc, int fr, int fq) const {
;     ...
;                 for (int m = 0; m < 4; ++m) {
;                     const int row = row0 + ai * 128 + m * 16;
; #pragma unroll
;                     for (int bj = 0; bj < 2; ++bj) {
;                         f32x4 v0 = acc[ai][bj][m][0], v1 = acc[ai][bj][m][1];
;                         if (rope) {
;                             const f32x4 c0 = *(const f32x4*)(cosT + (size_t)row * 16 + 8 * (fq & 1)), c1 = *(const f32x4*)(cosT + (size_t)row * 16 + 8 * (fq & 1) + 4);
;                             const f32x4 s0 = *(const f32x4*)(sinT + (size_t)row * 16 + 8 * (fq & 1)), s1 = *(const f32x4*)(sinT + (size_t)row * 16 + 8 * (fq & 1) + 4);
;                             const float sgn = (fq < 2) ? -1.0f : 1.0f;
; #pragma unroll
;                             for (int j = 0; j < 4; ++j) {
;                                 const float p0 = __shfl_xor(v0[j], 32), p1 = __shfl_xor(v1[j], 32);
;                                 v0[j] = v0[j] * c0[j] + sgn * p0 * s0[j];
;                                 v1[j] = v1[j] * c1[j] + sgn * p1 * s1[j];
;                             }
;                         }
;                         v0 *= sc; v1 *= sc;
;                         bf16_t* dst = P2 + (size_t)(arr0 + bj) * ((size_t)S * 128) + (size_t)row * 128 + cl;
;                         u32x4 w; w.x = cvt_pk_bf16(v0[0], v0[1]); w.y = cvt_pk_bf16(v0[2], v0[3]); w.z = cvt_pk_bf16(v1[0], v1[1]); w.w = cvt_pk_bf16(v1[2], v1[3]);
;                         *(u32x4*)dst = w;
.LBB0_233:
	v_lshlrev_b64 v[178:179], 8, v[178:179]
	v_pk_mul_f32 v[130:131], v[174:175], v[130:131]
	v_pk_mul_f32 v[128:129], v[170:171], v[128:129]
	v_pk_mul_f32 v[134:135], v[174:175], v[134:135]
	v_pk_mul_f32 v[132:133], v[170:171], v[132:133]
	v_lshl_add_u64 v[174:175], s[24:25], 0, v[178:179]
	v_lshl_add_u64 v[174:175], v[174:175], 0, v[148:149]
	v_cvt_pk_bf16_f32 v128, v128, v129
	v_cvt_pk_bf16_f32 v129, v130, v131
	v_cvt_pk_bf16_f32 v130, v132, v133
	v_cvt_pk_bf16_f32 v131, v134, v135
	global_store_dwordx4 v[174:175], v[128:131], off sc1
	v_mov_b64_e32 v[134:135], v[82:83]
	s_and_b64 vcc, exec, s[8:9]
	v_mov_b64_e32 v[130:131], v[86:87]
	v_mov_b64_e32 v[128:129], v[84:85]
	v_mov_b64_e32 v[132:133], v[80:81]
	s_cbranch_vccnz .LBB0_235
	global_load_dwordx4 v[130:133], v[176:177], off offset:16
	s_nop 0
	global_load_dwordx4 v[174:177], v[176:177], off
	s_nop 0
	global_load_dwordx4 v[182:185], v[172:173], off offset:16
	global_load_dwordx4 v[186:189], v[172:173], off
	v_cmp_lt_i32_e32 vcc, v209, v203
	s_waitcnt vmcnt(0)
	v_mul_f32_e32 v190, v82, v132
	v_cndmask_b32_e32 v128, v202, v209, vcc
	v_lshlrev_b32_e32 v156, 2, v128
	v_pk_mul_f32 v[172:173], v[84:85], v[174:175]
	v_pk_mul_f32 v[174:175], v[80:81], v[130:131]
	ds_bpermute_b32 v131, v156, v86
	ds_bpermute_b32 v157, v156, v82
	ds_bpermute_b32 v128, v156, v84
	ds_bpermute_b32 v129, v156, v85
	v_mul_f32_e32 v130, v86, v176
	s_waitcnt lgkmcnt(0)
	v_mul_f32_e32 v131, v146, v131
	v_mul_f32_e32 v176, v188, v131
	v_mul_f32_e32 v131, v146, v157
	v_mul_f32_e32 v192, v184, v131
	ds_bpermute_b32 v131, v156, v87
	ds_bpermute_b32 v132, v156, v83
	ds_bpermute_b32 v134, v156, v80
	ds_bpermute_b32 v135, v156, v81
	v_pk_mul_f32 v[128:129], v[146:147], v[128:129]
	s_waitcnt lgkmcnt(3)
	v_mul_f32_e32 v195, v146, v131
	v_mov_b32_e32 v188, v87
	v_mov_b32_e32 v194, v177
	v_pk_fma_f32 v[128:129], v[186:187], v[128:129], v[172:173]
	s_waitcnt lgkmcnt(2)
	v_mul_f32_e32 v173, v146, v132
	v_mov_b32_e32 v184, v83
	v_mov_b32_e32 v172, v133
	v_pk_mul_f32 v[188:189], v[188:189], v[194:195]
	v_pk_mul_f32 v[132:133], v[184:185], v[172:173]
	s_waitcnt lgkmcnt(0)
	v_pk_mul_f32 v[134:135], v[146:147], v[134:135]
	v_mov_b32_e32 v131, v188
	v_mov_b32_e32 v177, v189
	v_mov_b32_e32 v191, v132
	v_mov_b32_e32 v193, v133
	v_pk_add_f32 v[130:131], v[130:131], v[176:177]
	v_pk_fma_f32 v[132:133], v[182:183], v[134:135], v[174:175]
	v_pk_add_f32 v[134:135], v[190:191], v[192:193]
.LBB0_235:
	v_mov_b32_e32 v174, v170
	v_mov_b32_e32 v175, v170
	v_pk_mul_f32 v[130:131], v[174:175], v[130:131]
	v_pk_mul_f32 v[128:129], v[170:171], v[128:129]
	v_pk_mul_f32 v[134:135], v[174:175], v[134:135]
	v_pk_mul_f32 v[132:133], v[170:171], v[132:133]
	v_lshl_add_u64 v[172:173], s[26:27], 0, v[178:179]
	v_lshl_add_u64 v[172:173], v[172:173], 0, v[148:149]
	v_cvt_pk_bf16_f32 v128, v128, v129
	v_cvt_pk_bf16_f32 v129, v130, v131
	v_cvt_pk_bf16_f32 v130, v132, v133
	v_cvt_pk_bf16_f32 v131, v134, v135
	global_store_dwordx4 v[172:173], v[128:131], off sc1
	v_or_b32_e32 v178, 48, v168
	v_ashrrev_i32_e32 v179, 31, v178
	v_lshlrev_b64 v[128:129], 4, v[178:179]
	v_lshlrev_b64 v[128:129], 2, v[128:129]
	v_lshl_add_u64 v[176:177], v[160:161], 0, v[128:129]
	v_lshl_add_u64 v[172:173], v[162:163], 0, v[128:129]
	v_mov_b64_e32 v[130:131], v[78:79]
	v_mov_b64_e32 v[134:135], v[74:75]
	s_and_b64 vcc, exec, s[8:9]
	v_mov_b64_e32 v[128:129], v[76:77]
	v_mov_b64_e32 v[132:133], v[72:73]
	s_cbranch_vccnz .LBB0_237
	global_load_dwordx4 v[130:133], v[176:177], off offset:16
	global_load_dwordx4 v[182:185], v[176:177], off
	global_load_dwordx4 v[186:189], v[172:173], off offset:16
	global_load_dwordx4 v[190:193], v[172:173], off
	v_cmp_lt_i32_e32 vcc, v209, v203
	s_waitcnt vmcnt(0)
	v_pk_mul_f32 v[194:195], v[72:73], v[130:131]
	v_cndmask_b32_e32 v128, v202, v209, vcc
	v_lshlrev_b32_e32 v156, 2, v128
	ds_bpermute_b32 v131, v156, v78
	ds_bpermute_b32 v157, v156, v74
	ds_bpermute_b32 v128, v156, v76
	ds_bpermute_b32 v129, v156, v77
	v_mul_f32_e32 v130, v78, v184
	s_waitcnt lgkmcnt(0)
	v_mul_f32_e32 v131, v146, v131
	v_mul_f32_e32 v184, v192, v131
	v_mul_f32_e32 v131, v146, v157
	v_mul_f32_e32 v196, v74, v132
	v_mul_f32_e32 v218, v188, v131
	ds_bpermute_b32 v131, v156, v79
	ds_bpermute_b32 v132, v156, v75
	ds_bpermute_b32 v134, v156, v72
	ds_bpermute_b32 v135, v156, v73
	v_pk_mul_f32 v[182:183], v[76:77], v[182:183]
	v_pk_mul_f32 v[128:129], v[146:147], v[128:129]
	s_waitcnt lgkmcnt(3)
	v_mul_f32_e32 v221, v146, v131
	v_mov_b32_e32 v192, v79
	v_mov_b32_e32 v220, v185
	v_pk_fma_f32 v[128:129], v[190:191], v[128:129], v[182:183]
	s_waitcnt lgkmcnt(2)
	v_mul_f32_e32 v183, v146, v132
	v_mov_b32_e32 v188, v75
	v_mov_b32_e32 v182, v133
	v_pk_mul_f32 v[192:193], v[192:193], v[220:221]
	v_pk_mul_f32 v[132:133], v[188:189], v[182:183]
	s_waitcnt lgkmcnt(0)
	v_pk_mul_f32 v[134:135], v[146:147], v[134:135]
	v_mov_b32_e32 v131, v192
	v_mov_b32_e32 v185, v193
	v_mov_b32_e32 v197, v132
	v_mov_b32_e32 v219, v133
	v_pk_add_f32 v[130:131], v[130:131], v[184:185]
	v_pk_fma_f32 v[132:133], v[186:187], v[134:135], v[194:195]
	v_pk_add_f32 v[134:135], v[196:197], v[218:219]
;     DEVI void operator()(const f32x4 (&acc)[2][2][4][2], const Unit& u, int wr, int wc, int fr, int fq) const {
;     ...
;                 for (int m = 0; m < 4; ++m) {
;                     const int row = row0 + ai * 128 + m * 16;
; #pragma unroll
;                     for (int bj = 0; bj < 2; ++bj) {
;                         f32x4 v0 = acc[ai][bj][m][0], v1 = acc[ai][bj][m][1];
;                         if (rope) {
;                             const f32x4 c0 = *(const f32x4*)(cosT + (size_t)row * 16 + 8 * (fq & 1)), c1 = *(const f32x4*)(cosT + (size_t)row * 16 + 8 * (fq & 1) + 4);
;                             const f32x4 s0 = *(const f32x4*)(sinT + (size_t)row * 16 + 8 * (fq & 1)), s1 = *(const f32x4*)(sinT + (size_t)row * 16 + 8 * (fq & 1) + 4);
;                             const float sgn = (fq < 2) ? -1.0f : 1.0f;
; #pragma unroll
;                             for (int j = 0; j < 4; ++j) {
;                                 const float p0 = __shfl_xor(v0[j], 32), p1 = __shfl_xor(v1[j], 32);
;                                 v0[j] = v0[j] * c0[j] + sgn * p0 * s0[j];
;                                 v1[j] = v1[j] * c1[j] + sgn * p1 * s1[j];
;                             }
;                         }
;                         v0 *= sc; v1 *= sc;
;                         bf16_t* dst = P2 + (size_t)(arr0 + bj) * ((size_t)S * 128) + (size_t)row * 128 + cl;
;                         u32x4 w; w.x = cvt_pk_bf16(v0[0], v0[1]); w.y = cvt_pk_bf16(v0[2], v0[3]); w.z = cvt_pk_bf16(v1[0], v1[1]); w.w = cvt_pk_bf16(v1[2], v1[3]);
;                         *(u32x4*)dst = w;
.LBB0_237:
	v_lshlrev_b64 v[178:179], 8, v[178:179]
	v_pk_mul_f32 v[130:131], v[174:175], v[130:131]
	v_pk_mul_f32 v[128:129], v[170:171], v[128:129]
	v_pk_mul_f32 v[134:135], v[174:175], v[134:135]
	v_pk_mul_f32 v[132:133], v[170:171], v[132:133]
	v_lshl_add_u64 v[174:175], s[24:25], 0, v[178:179]
	v_lshl_add_u64 v[174:175], v[174:175], 0, v[148:149]
	v_cvt_pk_bf16_f32 v128, v128, v129
	v_cvt_pk_bf16_f32 v129, v130, v131
	v_cvt_pk_bf16_f32 v130, v132, v133
	v_cvt_pk_bf16_f32 v131, v134, v135
	global_store_dwordx4 v[174:175], v[128:131], off sc1
	v_mov_b64_e32 v[134:135], v[66:67]
	s_and_b64 vcc, exec, s[8:9]
	v_mov_b64_e32 v[130:131], v[70:71]
	v_mov_b64_e32 v[128:129], v[68:69]
	v_mov_b64_e32 v[132:133], v[64:65]
	s_cbranch_vccnz .LBB0_239
	global_load_dwordx4 v[130:133], v[176:177], off offset:16
	s_nop 0
	global_load_dwordx4 v[174:177], v[176:177], off
	s_nop 0
	global_load_dwordx4 v[182:185], v[172:173], off offset:16
	global_load_dwordx4 v[186:189], v[172:173], off
	v_cmp_lt_i32_e32 vcc, v209, v203
	s_waitcnt vmcnt(0)
	v_mul_f32_e32 v190, v66, v132
	v_cndmask_b32_e32 v128, v202, v209, vcc
	v_lshlrev_b32_e32 v156, 2, v128
	v_pk_mul_f32 v[172:173], v[68:69], v[174:175]
	v_pk_mul_f32 v[174:175], v[64:65], v[130:131]
	ds_bpermute_b32 v131, v156, v70
	ds_bpermute_b32 v157, v156, v66
	ds_bpermute_b32 v128, v156, v68
	ds_bpermute_b32 v129, v156, v69
	v_mul_f32_e32 v130, v70, v176
	s_waitcnt lgkmcnt(0)
	v_mul_f32_e32 v131, v146, v131
	v_mul_f32_e32 v176, v188, v131
	v_mul_f32_e32 v131, v146, v157
	v_mul_f32_e32 v192, v184, v131
	ds_bpermute_b32 v131, v156, v71
	ds_bpermute_b32 v132, v156, v67
	ds_bpermute_b32 v134, v156, v64
	ds_bpermute_b32 v135, v156, v65
	v_pk_mul_f32 v[128:129], v[146:147], v[128:129]
	s_waitcnt lgkmcnt(3)
	v_mul_f32_e32 v195, v146, v131
	v_mov_b32_e32 v188, v71
	v_mov_b32_e32 v194, v177
	v_pk_fma_f32 v[128:129], v[186:187], v[128:129], v[172:173]
	s_waitcnt lgkmcnt(2)
	v_mul_f32_e32 v173, v146, v132
	v_mov_b32_e32 v184, v67
	v_mov_b32_e32 v172, v133
	v_pk_mul_f32 v[188:189], v[188:189], v[194:195]
	v_pk_mul_f32 v[132:133], v[184:185], v[172:173]
	s_waitcnt lgkmcnt(0)
	v_pk_mul_f32 v[134:135], v[146:147], v[134:135]
	v_mov_b32_e32 v131, v188
	v_mov_b32_e32 v177, v189
	v_mov_b32_e32 v191, v132
	v_mov_b32_e32 v193, v133
	v_pk_add_f32 v[130:131], v[130:131], v[176:177]
	v_pk_fma_f32 v[132:133], v[182:183], v[134:135], v[174:175]
	v_pk_add_f32 v[134:135], v[190:191], v[192:193]
.LBB0_239:
	v_mov_b32_e32 v174, v170
	v_mov_b32_e32 v175, v170
	v_pk_mul_f32 v[130:131], v[174:175], v[130:131]
	v_pk_mul_f32 v[128:129], v[170:171], v[128:129]
	v_pk_mul_f32 v[134:135], v[174:175], v[134:135]
	v_pk_mul_f32 v[132:133], v[170:171], v[132:133]
	v_lshl_add_u64 v[172:173], s[26:27], 0, v[178:179]
	v_lshl_add_u64 v[172:173], v[172:173], 0, v[148:149]
	v_cvt_pk_bf16_f32 v128, v128, v129
	v_cvt_pk_bf16_f32 v129, v130, v131
	v_cvt_pk_bf16_f32 v130, v132, v133
	v_cvt_pk_bf16_f32 v131, v134, v135
	global_store_dwordx4 v[172:173], v[128:131], off sc1
	v_add_u32_e32 v178, 0x80, v168
	v_ashrrev_i32_e32 v179, 31, v178
	v_lshlrev_b64 v[128:129], 4, v[178:179]
	v_lshlrev_b64 v[128:129], 2, v[128:129]
	v_lshl_add_u64 v[176:177], v[160:161], 0, v[128:129]
	v_lshl_add_u64 v[172:173], v[162:163], 0, v[128:129]
	v_mov_b64_e32 v[130:131], v[62:63]
	v_mov_b64_e32 v[134:135], v[58:59]
	s_and_b64 vcc, exec, s[8:9]
	v_mov_b64_e32 v[128:129], v[60:61]
	v_mov_b64_e32 v[132:133], v[56:57]
	s_cbranch_vccnz .LBB0_241
	global_load_dwordx4 v[130:133], v[176:177], off offset:16
	global_load_dwordx4 v[182:185], v[176:177], off
	global_load_dwordx4 v[186:189], v[172:173], off offset:16
	global_load_dwordx4 v[190:193], v[172:173], off
	v_cmp_lt_i32_e32 vcc, v209, v203
	s_waitcnt vmcnt(0)
	v_pk_mul_f32 v[194:195], v[56:57], v[130:131]
	v_cndmask_b32_e32 v128, v202, v209, vcc
	v_lshlrev_b32_e32 v156, 2, v128
	ds_bpermute_b32 v131, v156, v62
	ds_bpermute_b32 v157, v156, v58
	ds_bpermute_b32 v128, v156, v60
	ds_bpermute_b32 v129, v156, v61
	v_mul_f32_e32 v130, v62, v184
	s_waitcnt lgkmcnt(0)
	v_mul_f32_e32 v131, v146, v131
	v_mul_f32_e32 v184, v192, v131
	v_mul_f32_e32 v131, v146, v157
	v_mul_f32_e32 v196, v58, v132
	v_mul_f32_e32 v218, v188, v131
	ds_bpermute_b32 v131, v156, v63
	ds_bpermute_b32 v132, v156, v59
	ds_bpermute_b32 v134, v156, v56
	ds_bpermute_b32 v135, v156, v57
	v_pk_mul_f32 v[182:183], v[60:61], v[182:183]
	v_pk_mul_f32 v[128:129], v[146:147], v[128:129]
	s_waitcnt lgkmcnt(3)
	v_mul_f32_e32 v221, v146, v131
	v_mov_b32_e32 v192, v63
	v_mov_b32_e32 v220, v185
	v_pk_fma_f32 v[128:129], v[190:191], v[128:129], v[182:183]
	s_waitcnt lgkmcnt(2)
	v_mul_f32_e32 v183, v146, v132
	v_mov_b32_e32 v188, v59
	v_mov_b32_e32 v182, v133
	v_pk_mul_f32 v[192:193], v[192:193], v[220:221]
	v_pk_mul_f32 v[132:133], v[188:189], v[182:183]
	s_waitcnt lgkmcnt(0)
	v_pk_mul_f32 v[134:135], v[146:147], v[134:135]
	v_mov_b32_e32 v131, v192
	v_mov_b32_e32 v185, v193
	v_mov_b32_e32 v197, v132
	v_mov_b32_e32 v219, v133
	v_pk_add_f32 v[130:131], v[130:131], v[184:185]
	v_pk_fma_f32 v[132:133], v[186:187], v[134:135], v[194:195]
	v_pk_add_f32 v[134:135], v[196:197], v[218:219]
;     DEVI void operator()(const f32x4 (&acc)[2][2][4][2], const Unit& u, int wr, int wc, int fr, int fq) const {
;     ...
;                 for (int m = 0; m < 4; ++m) {
;                     const int row = row0 + ai * 128 + m * 16;
; #pragma unroll
;                     for (int bj = 0; bj < 2; ++bj) {
;                         f32x4 v0 = acc[ai][bj][m][0], v1 = acc[ai][bj][m][1];
;                         if (rope) {
;                             const f32x4 c0 = *(const f32x4*)(cosT + (size_t)row * 16 + 8 * (fq & 1)), c1 = *(const f32x4*)(cosT + (size_t)row * 16 + 8 * (fq & 1) + 4);
;                             const f32x4 s0 = *(const f32x4*)(sinT + (size_t)row * 16 + 8 * (fq & 1)), s1 = *(const f32x4*)(sinT + (size_t)row * 16 + 8 * (fq & 1) + 4);
;                             const float sgn = (fq < 2) ? -1.0f : 1.0f;
; #pragma unroll
;                             for (int j = 0; j < 4; ++j) {
;                                 const float p0 = __shfl_xor(v0[j], 32), p1 = __shfl_xor(v1[j], 32);
;                                 v0[j] = v0[j] * c0[j] + sgn * p0 * s0[j];
;                                 v1[j] = v1[j] * c1[j] + sgn * p1 * s1[j];
;                             }
;                         }
;                         v0 *= sc; v1 *= sc;
;                         bf16_t* dst = P2 + (size_t)(arr0 + bj) * ((size_t)S * 128) + (size_t)row * 128 + cl;
;                         u32x4 w; w.x = cvt_pk_bf16(v0[0], v0[1]); w.y = cvt_pk_bf16(v0[2], v0[3]); w.z = cvt_pk_bf16(v1[0], v1[1]); w.w = cvt_pk_bf16(v1[2], v1[3]);
;                         *(u32x4*)dst = w;
.LBB0_241:
	v_lshlrev_b64 v[178:179], 8, v[178:179]
	v_pk_mul_f32 v[130:131], v[174:175], v[130:131]
	v_pk_mul_f32 v[128:129], v[170:171], v[128:129]
	v_pk_mul_f32 v[134:135], v[174:175], v[134:135]
	v_pk_mul_f32 v[132:133], v[170:171], v[132:133]
	v_lshl_add_u64 v[174:175], s[24:25], 0, v[178:179]
	v_lshl_add_u64 v[174:175], v[174:175], 0, v[148:149]
	v_cvt_pk_bf16_f32 v128, v128, v129
	v_cvt_pk_bf16_f32 v129, v130, v131
	v_cvt_pk_bf16_f32 v130, v132, v133
	v_cvt_pk_bf16_f32 v131, v134, v135
	global_store_dwordx4 v[174:175], v[128:131], off sc1
	v_mov_b64_e32 v[134:135], v[50:51]
	s_and_b64 vcc, exec, s[8:9]
	v_mov_b64_e32 v[130:131], v[54:55]
	v_mov_b64_e32 v[128:129], v[52:53]
	v_mov_b64_e32 v[132:133], v[48:49]
	s_cbranch_vccnz .LBB0_243
	global_load_dwordx4 v[130:133], v[176:177], off offset:16
	s_nop 0
	global_load_dwordx4 v[174:177], v[176:177], off
	s_nop 0
	global_load_dwordx4 v[182:185], v[172:173], off offset:16
	global_load_dwordx4 v[186:189], v[172:173], off
	v_cmp_lt_i32_e32 vcc, v209, v203
	s_waitcnt vmcnt(0)
	v_mul_f32_e32 v190, v50, v132
	v_cndmask_b32_e32 v128, v202, v209, vcc
	v_lshlrev_b32_e32 v156, 2, v128
	v_pk_mul_f32 v[172:173], v[52:53], v[174:175]
	v_pk_mul_f32 v[174:175], v[48:49], v[130:131]
	ds_bpermute_b32 v131, v156, v54
	ds_bpermute_b32 v157, v156, v50
	ds_bpermute_b32 v128, v156, v52
	ds_bpermute_b32 v129, v156, v53
	v_mul_f32_e32 v130, v54, v176
	s_waitcnt lgkmcnt(0)
	v_mul_f32_e32 v131, v146, v131
	v_mul_f32_e32 v176, v188, v131
	v_mul_f32_e32 v131, v146, v157
	v_mul_f32_e32 v192, v184, v131
	ds_bpermute_b32 v131, v156, v55
	ds_bpermute_b32 v132, v156, v51
	ds_bpermute_b32 v134, v156, v48
	ds_bpermute_b32 v135, v156, v49
	v_pk_mul_f32 v[128:129], v[146:147], v[128:129]
	s_waitcnt lgkmcnt(3)
	v_mul_f32_e32 v195, v146, v131
	v_mov_b32_e32 v188, v55
	v_mov_b32_e32 v194, v177
	v_pk_fma_f32 v[128:129], v[186:187], v[128:129], v[172:173]
	s_waitcnt lgkmcnt(2)
	v_mul_f32_e32 v173, v146, v132
	v_mov_b32_e32 v184, v51
	v_mov_b32_e32 v172, v133
	v_pk_mul_f32 v[188:189], v[188:189], v[194:195]
	v_pk_mul_f32 v[132:133], v[184:185], v[172:173]
	s_waitcnt lgkmcnt(0)
	v_pk_mul_f32 v[134:135], v[146:147], v[134:135]
	v_mov_b32_e32 v131, v188
	v_mov_b32_e32 v177, v189
	v_mov_b32_e32 v191, v132
	v_mov_b32_e32 v193, v133
	v_pk_add_f32 v[130:131], v[130:131], v[176:177]
	v_pk_fma_f32 v[132:133], v[182:183], v[134:135], v[174:175]
	v_pk_add_f32 v[134:135], v[190:191], v[192:193]
.LBB0_243:
	v_mov_b32_e32 v174, v170
	v_mov_b32_e32 v175, v170
	v_pk_mul_f32 v[130:131], v[174:175], v[130:131]
	v_pk_mul_f32 v[128:129], v[170:171], v[128:129]
	v_pk_mul_f32 v[134:135], v[174:175], v[134:135]
	v_pk_mul_f32 v[132:133], v[170:171], v[132:133]
	v_lshl_add_u64 v[172:173], s[26:27], 0, v[178:179]
	v_lshl_add_u64 v[172:173], v[172:173], 0, v[148:149]
	v_cvt_pk_bf16_f32 v128, v128, v129
	v_cvt_pk_bf16_f32 v129, v130, v131
	v_cvt_pk_bf16_f32 v130, v132, v133
	v_cvt_pk_bf16_f32 v131, v134, v135
	global_store_dwordx4 v[172:173], v[128:131], off sc1
	v_add_u32_e32 v178, 0x90, v168
	v_ashrrev_i32_e32 v179, 31, v178
	v_lshlrev_b64 v[128:129], 4, v[178:179]
	v_lshlrev_b64 v[128:129], 2, v[128:129]
	v_lshl_add_u64 v[176:177], v[160:161], 0, v[128:129]
	v_lshl_add_u64 v[172:173], v[162:163], 0, v[128:129]
	v_mov_b64_e32 v[130:131], v[46:47]
	v_mov_b64_e32 v[134:135], v[42:43]
	s_and_b64 vcc, exec, s[8:9]
	v_mov_b64_e32 v[128:129], v[44:45]
	v_mov_b64_e32 v[132:133], v[40:41]
	s_cbranch_vccnz .LBB0_245
	global_load_dwordx4 v[130:133], v[176:177], off offset:16
	global_load_dwordx4 v[182:185], v[176:177], off
	global_load_dwordx4 v[186:189], v[172:173], off offset:16
	global_load_dwordx4 v[190:193], v[172:173], off
	v_cmp_lt_i32_e32 vcc, v209, v203
	s_waitcnt vmcnt(0)
	v_pk_mul_f32 v[194:195], v[40:41], v[130:131]
	v_cndmask_b32_e32 v128, v202, v209, vcc
	v_lshlrev_b32_e32 v156, 2, v128
	ds_bpermute_b32 v131, v156, v46
	ds_bpermute_b32 v157, v156, v42
	ds_bpermute_b32 v128, v156, v44
	ds_bpermute_b32 v129, v156, v45
	v_mul_f32_e32 v130, v46, v184
	s_waitcnt lgkmcnt(0)
	v_mul_f32_e32 v131, v146, v131
	v_mul_f32_e32 v184, v192, v131
	v_mul_f32_e32 v131, v146, v157
	v_mul_f32_e32 v196, v42, v132
	v_mul_f32_e32 v218, v188, v131
	ds_bpermute_b32 v131, v156, v47
	ds_bpermute_b32 v132, v156, v43
	ds_bpermute_b32 v134, v156, v40
	ds_bpermute_b32 v135, v156, v41
	v_pk_mul_f32 v[182:183], v[44:45], v[182:183]
	v_pk_mul_f32 v[128:129], v[146:147], v[128:129]
	s_waitcnt lgkmcnt(3)
	v_mul_f32_e32 v221, v146, v131
	v_mov_b32_e32 v192, v47
	v_mov_b32_e32 v220, v185
	v_pk_fma_f32 v[128:129], v[190:191], v[128:129], v[182:183]
	s_waitcnt lgkmcnt(2)
	v_mul_f32_e32 v183, v146, v132
	v_mov_b32_e32 v188, v43
	v_mov_b32_e32 v182, v133
	v_pk_mul_f32 v[192:193], v[192:193], v[220:221]
	v_pk_mul_f32 v[132:133], v[188:189], v[182:183]
	s_waitcnt lgkmcnt(0)
	v_pk_mul_f32 v[134:135], v[146:147], v[134:135]
	v_mov_b32_e32 v131, v192
	v_mov_b32_e32 v185, v193
	v_mov_b32_e32 v197, v132
	v_mov_b32_e32 v219, v133
	v_pk_add_f32 v[130:131], v[130:131], v[184:185]
	v_pk_fma_f32 v[132:133], v[186:187], v[134:135], v[194:195]
	v_pk_add_f32 v[134:135], v[196:197], v[218:219]
;     DEVI void operator()(const f32x4 (&acc)[2][2][4][2], const Unit& u, int wr, int wc, int fr, int fq) const {
;     ...
;                 for (int m = 0; m < 4; ++m) {
;                     const int row = row0 + ai * 128 + m * 16;
; #pragma unroll
;                     for (int bj = 0; bj < 2; ++bj) {
;                         f32x4 v0 = acc[ai][bj][m][0], v1 = acc[ai][bj][m][1];
;                         if (rope) {
;                             const f32x4 c0 = *(const f32x4*)(cosT + (size_t)row * 16 + 8 * (fq & 1)), c1 = *(const f32x4*)(cosT + (size_t)row * 16 + 8 * (fq & 1) + 4);
;                             const f32x4 s0 = *(const f32x4*)(sinT + (size_t)row * 16 + 8 * (fq & 1)), s1 = *(const f32x4*)(sinT + (size_t)row * 16 + 8 * (fq & 1) + 4);
;                             const float sgn = (fq < 2) ? -1.0f : 1.0f;
; #pragma unroll
;                             for (int j = 0; j < 4; ++j) {
;                                 const float p0 = __shfl_xor(v0[j], 32), p1 = __shfl_xor(v1[j], 32);
;                                 v0[j] = v0[j] * c0[j] + sgn * p0 * s0[j];
;                                 v1[j] = v1[j] * c1[j] + sgn * p1 * s1[j];
;                             }
;                         }
;                         v0 *= sc; v1 *= sc;
;                         bf16_t* dst = P2 + (size_t)(arr0 + bj) * ((size_t)S * 128) + (size_t)row * 128 + cl;
;                         u32x4 w; w.x = cvt_pk_bf16(v0[0], v0[1]); w.y = cvt_pk_bf16(v0[2], v0[3]); w.z = cvt_pk_bf16(v1[0], v1[1]); w.w = cvt_pk_bf16(v1[2], v1[3]);
;                         *(u32x4*)dst = w;
;                     }
.LBB0_245:
	v_lshlrev_b64 v[178:179], 8, v[178:179]
	v_pk_mul_f32 v[130:131], v[174:175], v[130:131]
	v_pk_mul_f32 v[128:129], v[170:171], v[128:129]
	v_pk_mul_f32 v[134:135], v[174:175], v[134:135]
	v_pk_mul_f32 v[132:133], v[170:171], v[132:133]
	v_lshl_add_u64 v[174:175], s[24:25], 0, v[178:179]
	v_lshl_add_u64 v[174:175], v[174:175], 0, v[148:149]
	v_cvt_pk_bf16_f32 v128, v128, v129
	v_cvt_pk_bf16_f32 v129, v130, v131
	v_cvt_pk_bf16_f32 v130, v132, v133
	v_cvt_pk_bf16_f32 v131, v134, v135
	global_store_dwordx4 v[174:175], v[128:131], off sc1
	v_mov_b64_e32 v[134:135], v[34:35]
	s_and_b64 vcc, exec, s[8:9]
	v_mov_b64_e32 v[130:131], v[38:39]
	v_mov_b64_e32 v[128:129], v[36:37]
	v_mov_b64_e32 v[132:133], v[32:33]
	s_cbranch_vccnz .LBB0_247
	global_load_dwordx4 v[130:133], v[176:177], off offset:16
	s_nop 0
	global_load_dwordx4 v[174:177], v[176:177], off
	s_nop 0
	global_load_dwordx4 v[182:185], v[172:173], off offset:16
	global_load_dwordx4 v[186:189], v[172:173], off
	v_cmp_lt_i32_e32 vcc, v209, v203
	s_waitcnt vmcnt(0)
	v_mul_f32_e32 v190, v34, v132
	v_cndmask_b32_e32 v128, v202, v209, vcc
	v_lshlrev_b32_e32 v156, 2, v128
	v_pk_mul_f32 v[172:173], v[36:37], v[174:175]
	v_pk_mul_f32 v[174:175], v[32:33], v[130:131]
	ds_bpermute_b32 v131, v156, v38
	ds_bpermute_b32 v157, v156, v34
	ds_bpermute_b32 v128, v156, v36
	ds_bpermute_b32 v129, v156, v37
	v_mul_f32_e32 v130, v38, v176
	s_waitcnt lgkmcnt(0)
	v_mul_f32_e32 v131, v146, v131
	v_mul_f32_e32 v176, v188, v131
	v_mul_f32_e32 v131, v146, v157
	v_mul_f32_e32 v192, v184, v131
	ds_bpermute_b32 v131, v156, v39
	ds_bpermute_b32 v132, v156, v35
	ds_bpermute_b32 v134, v156, v32
	ds_bpermute_b32 v135, v156, v33
	v_pk_mul_f32 v[128:129], v[146:147], v[128:129]
	s_waitcnt lgkmcnt(3)
	v_mul_f32_e32 v195, v146, v131
	v_mov_b32_e32 v188, v39
	v_mov_b32_e32 v194, v177
	v_pk_fma_f32 v[128:129], v[186:187], v[128:129], v[172:173]
	s_waitcnt lgkmcnt(2)
	v_mul_f32_e32 v173, v146, v132
	v_mov_b32_e32 v184, v35
	v_mov_b32_e32 v172, v133
	v_pk_mul_f32 v[188:189], v[188:189], v[194:195]
	v_pk_mul_f32 v[132:133], v[184:185], v[172:173]
	s_waitcnt lgkmcnt(0)
	v_pk_mul_f32 v[134:135], v[146:147], v[134:135]
	v_mov_b32_e32 v131, v188
	v_mov_b32_e32 v177, v189
	v_mov_b32_e32 v191, v132
	v_mov_b32_e32 v193, v133
	v_pk_add_f32 v[130:131], v[130:131], v[176:177]
	v_pk_fma_f32 v[132:133], v[182:183], v[134:135], v[174:175]
	v_pk_add_f32 v[134:135], v[190:191], v[192:193]
.LBB0_247:
	v_mov_b32_e32 v174, v170
	v_mov_b32_e32 v175, v170
	v_pk_mul_f32 v[130:131], v[174:175], v[130:131]
	v_pk_mul_f32 v[128:129], v[170:171], v[128:129]
	v_pk_mul_f32 v[134:135], v[174:175], v[134:135]
	v_pk_mul_f32 v[132:133], v[170:171], v[132:133]
	v_lshl_add_u64 v[172:173], s[26:27], 0, v[178:179]
	v_lshl_add_u64 v[172:173], v[172:173], 0, v[148:149]
	v_cvt_pk_bf16_f32 v128, v128, v129
	v_cvt_pk_bf16_f32 v129, v130, v131
	v_cvt_pk_bf16_f32 v130, v132, v133
	v_cvt_pk_bf16_f32 v131, v134, v135
	global_store_dwordx4 v[172:173], v[128:131], off sc1
	v_add_u32_e32 v178, 0xa0, v168
	v_ashrrev_i32_e32 v179, 31, v178
	v_lshlrev_b64 v[128:129], 4, v[178:179]
	v_lshlrev_b64 v[128:129], 2, v[128:129]
	v_lshl_add_u64 v[176:177], v[160:161], 0, v[128:129]
	v_lshl_add_u64 v[172:173], v[162:163], 0, v[128:129]
	v_mov_b64_e32 v[130:131], v[30:31]
	v_mov_b64_e32 v[134:135], v[26:27]
	s_and_b64 vcc, exec, s[8:9]
	v_mov_b64_e32 v[128:129], v[28:29]
	v_mov_b64_e32 v[132:133], v[24:25]
	s_cbranch_vccnz .LBB0_249
	global_load_dwordx4 v[130:133], v[176:177], off offset:16
	global_load_dwordx4 v[182:185], v[176:177], off
	global_load_dwordx4 v[186:189], v[172:173], off offset:16
	global_load_dwordx4 v[190:193], v[172:173], off
	v_cmp_lt_i32_e32 vcc, v209, v203
	s_waitcnt vmcnt(0)
	v_pk_mul_f32 v[194:195], v[24:25], v[130:131]
	v_cndmask_b32_e32 v128, v202, v209, vcc
	v_lshlrev_b32_e32 v156, 2, v128
	ds_bpermute_b32 v131, v156, v30
	ds_bpermute_b32 v157, v156, v26
	ds_bpermute_b32 v128, v156, v28
	ds_bpermute_b32 v129, v156, v29
	v_mul_f32_e32 v130, v30, v184
	s_waitcnt lgkmcnt(0)
	v_mul_f32_e32 v131, v146, v131
	v_mul_f32_e32 v184, v192, v131
	v_mul_f32_e32 v131, v146, v157
	v_mul_f32_e32 v196, v26, v132
	v_mul_f32_e32 v218, v188, v131
	ds_bpermute_b32 v131, v156, v31
	ds_bpermute_b32 v132, v156, v27
	ds_bpermute_b32 v134, v156, v24
	ds_bpermute_b32 v135, v156, v25
	v_pk_mul_f32 v[182:183], v[28:29], v[182:183]
	v_pk_mul_f32 v[128:129], v[146:147], v[128:129]
	s_waitcnt lgkmcnt(3)
	v_mul_f32_e32 v221, v146, v131
	v_mov_b32_e32 v192, v31
	v_mov_b32_e32 v220, v185
	v_pk_fma_f32 v[128:129], v[190:191], v[128:129], v[182:183]
	s_waitcnt lgkmcnt(2)
	v_mul_f32_e32 v183, v146, v132
	v_mov_b32_e32 v188, v27
	v_mov_b32_e32 v182, v133
	v_pk_mul_f32 v[192:193], v[192:193], v[220:221]
	v_pk_mul_f32 v[132:133], v[188:189], v[182:183]
	s_waitcnt lgkmcnt(0)
	v_pk_mul_f32 v[134:135], v[146:147], v[134:135]
	v_mov_b32_e32 v131, v192
	v_mov_b32_e32 v185, v193
	v_mov_b32_e32 v197, v132
	v_mov_b32_e32 v219, v133
	v_pk_add_f32 v[130:131], v[130:131], v[184:185]
	v_pk_fma_f32 v[132:133], v[186:187], v[134:135], v[194:195]
	v_pk_add_f32 v[134:135], v[196:197], v[218:219]
;     DEVI void operator()(const f32x4 (&acc)[2][2][4][2], const Unit& u, int wr, int wc, int fr, int fq) const {
;     ...
;                 for (int m = 0; m < 4; ++m) {
;                     const int row = row0 + ai * 128 + m * 16;
; #pragma unroll
;                     for (int bj = 0; bj < 2; ++bj) {
;                         f32x4 v0 = acc[ai][bj][m][0], v1 = acc[ai][bj][m][1];
;                         if (rope) {
;                             const f32x4 c0 = *(const f32x4*)(cosT + (size_t)row * 16 + 8 * (fq & 1)), c1 = *(const f32x4*)(cosT + (size_t)row * 16 + 8 * (fq & 1) + 4);
;                             const f32x4 s0 = *(const f32x4*)(sinT + (size_t)row * 16 + 8 * (fq & 1)), s1 = *(const f32x4*)(sinT + (size_t)row * 16 + 8 * (fq & 1) + 4);
;                             const float sgn = (fq < 2) ? -1.0f : 1.0f;
; #pragma unroll
;                             for (int j = 0; j < 4; ++j) {
;                                 const float p0 = __shfl_xor(v0[j], 32), p1 = __shfl_xor(v1[j], 32);
;                                 v0[j] = v0[j] * c0[j] + sgn * p0 * s0[j];
;                                 v1[j] = v1[j] * c1[j] + sgn * p1 * s1[j];
;                             }
;                         }
;                         v0 *= sc; v1 *= sc;
;                         bf16_t* dst = P2 + (size_t)(arr0 + bj) * ((size_t)S * 128) + (size_t)row * 128 + cl;
;                         u32x4 w; w.x = cvt_pk_bf16(v0[0], v0[1]); w.y = cvt_pk_bf16(v0[2], v0[3]); w.z = cvt_pk_bf16(v1[0], v1[1]); w.w = cvt_pk_bf16(v1[2], v1[3]);
;                         *(u32x4*)dst = w;
;                     }
.LBB0_249:
	v_lshlrev_b64 v[178:179], 8, v[178:179]
	v_pk_mul_f32 v[130:131], v[174:175], v[130:131]
	v_pk_mul_f32 v[128:129], v[170:171], v[128:129]
	v_pk_mul_f32 v[134:135], v[174:175], v[134:135]
	v_pk_mul_f32 v[132:133], v[170:171], v[132:133]
	v_lshl_add_u64 v[174:175], s[24:25], 0, v[178:179]
	v_lshl_add_u64 v[174:175], v[174:175], 0, v[148:149]
	v_cvt_pk_bf16_f32 v128, v128, v129
	v_cvt_pk_bf16_f32 v129, v130, v131
	v_cvt_pk_bf16_f32 v130, v132, v133
	v_cvt_pk_bf16_f32 v131, v134, v135
	global_store_dwordx4 v[174:175], v[128:131], off sc1
	v_mov_b64_e32 v[134:135], v[18:19]
	s_and_b64 vcc, exec, s[8:9]
	v_mov_b64_e32 v[130:131], v[22:23]
	v_mov_b64_e32 v[128:129], v[20:21]
	v_mov_b64_e32 v[132:133], v[16:17]
	s_cbranch_vccnz .LBB0_251
	global_load_dwordx4 v[130:133], v[176:177], off offset:16
	s_nop 0
	global_load_dwordx4 v[174:177], v[176:177], off
	s_nop 0
	global_load_dwordx4 v[182:185], v[172:173], off offset:16
	global_load_dwordx4 v[186:189], v[172:173], off
	v_cmp_lt_i32_e32 vcc, v209, v203
	s_waitcnt vmcnt(0)
	v_mul_f32_e32 v190, v18, v132
	v_cndmask_b32_e32 v128, v202, v209, vcc
	v_lshlrev_b32_e32 v156, 2, v128
	v_pk_mul_f32 v[172:173], v[20:21], v[174:175]
	v_pk_mul_f32 v[174:175], v[16:17], v[130:131]
	ds_bpermute_b32 v131, v156, v22
	ds_bpermute_b32 v157, v156, v18
	ds_bpermute_b32 v128, v156, v20
	ds_bpermute_b32 v129, v156, v21
	v_mul_f32_e32 v130, v22, v176
	s_waitcnt lgkmcnt(0)
	v_mul_f32_e32 v131, v146, v131
	v_mul_f32_e32 v176, v188, v131
	v_mul_f32_e32 v131, v146, v157
	v_mul_f32_e32 v192, v184, v131
	ds_bpermute_b32 v131, v156, v23
	ds_bpermute_b32 v132, v156, v19
	ds_bpermute_b32 v134, v156, v16
	ds_bpermute_b32 v135, v156, v17
	v_pk_mul_f32 v[128:129], v[146:147], v[128:129]
	s_waitcnt lgkmcnt(3)
	v_mul_f32_e32 v195, v146, v131
	v_mov_b32_e32 v188, v23
	v_mov_b32_e32 v194, v177
	v_pk_fma_f32 v[128:129], v[186:187], v[128:129], v[172:173]
	s_waitcnt lgkmcnt(2)
	v_mul_f32_e32 v173, v146, v132
	v_mov_b32_e32 v184, v19
	v_mov_b32_e32 v172, v133
	v_pk_mul_f32 v[188:189], v[188:189], v[194:195]
	v_pk_mul_f32 v[132:133], v[184:185], v[172:173]
	s_waitcnt lgkmcnt(0)
	v_pk_mul_f32 v[134:135], v[146:147], v[134:135]
	v_mov_b32_e32 v131, v188
	v_mov_b32_e32 v177, v189
	v_mov_b32_e32 v191, v132
	v_mov_b32_e32 v193, v133
	v_pk_add_f32 v[130:131], v[130:131], v[176:177]
	v_pk_fma_f32 v[132:133], v[182:183], v[134:135], v[174:175]
	v_pk_add_f32 v[134:135], v[190:191], v[192:193]
.LBB0_251:
	v_mov_b32_e32 v174, v170
	v_mov_b32_e32 v175, v170
	v_pk_mul_f32 v[130:131], v[174:175], v[130:131]
	v_pk_mul_f32 v[128:129], v[170:171], v[128:129]
	v_pk_mul_f32 v[134:135], v[174:175], v[134:135]
	v_pk_mul_f32 v[132:133], v[170:171], v[132:133]
	v_lshl_add_u64 v[172:173], s[26:27], 0, v[178:179]
	v_lshl_add_u64 v[172:173], v[172:173], 0, v[148:149]
	v_cvt_pk_bf16_f32 v128, v128, v129
	v_cvt_pk_bf16_f32 v129, v130, v131
	v_cvt_pk_bf16_f32 v130, v132, v133
	v_cvt_pk_bf16_f32 v131, v134, v135
	global_store_dwordx4 v[172:173], v[128:131], off sc1
	v_add_u32_e32 v178, 0xb0, v168
	v_ashrrev_i32_e32 v179, 31, v178
	v_lshlrev_b64 v[128:129], 4, v[178:179]
	v_lshlrev_b64 v[128:129], 2, v[128:129]
	v_lshl_add_u64 v[176:177], v[160:161], 0, v[128:129]
	v_lshl_add_u64 v[172:173], v[162:163], 0, v[128:129]
	v_mov_b64_e32 v[130:131], v[14:15]
	v_mov_b64_e32 v[134:135], v[10:11]
	s_and_b64 vcc, exec, s[8:9]
	v_mov_b64_e32 v[128:129], v[12:13]
	v_mov_b64_e32 v[132:133], v[8:9]
	s_cbranch_vccnz .LBB0_253
	global_load_dwordx4 v[130:133], v[176:177], off offset:16
	global_load_dwordx4 v[182:185], v[176:177], off
	global_load_dwordx4 v[186:189], v[172:173], off offset:16
	global_load_dwordx4 v[190:193], v[172:173], off
	v_cmp_lt_i32_e32 vcc, v209, v203
	s_waitcnt vmcnt(0)
	v_pk_mul_f32 v[194:195], v[8:9], v[130:131]
	v_cndmask_b32_e32 v128, v202, v209, vcc
	v_lshlrev_b32_e32 v156, 2, v128
	ds_bpermute_b32 v131, v156, v14
	ds_bpermute_b32 v157, v156, v10
	ds_bpermute_b32 v128, v156, v12
	ds_bpermute_b32 v129, v156, v13
	v_mul_f32_e32 v130, v14, v184
	s_waitcnt lgkmcnt(0)
	v_mul_f32_e32 v131, v146, v131
	v_mul_f32_e32 v184, v192, v131
	v_mul_f32_e32 v131, v146, v157
	v_mul_f32_e32 v196, v10, v132
	v_mul_f32_e32 v218, v188, v131
	ds_bpermute_b32 v131, v156, v15
	ds_bpermute_b32 v132, v156, v11
	ds_bpermute_b32 v134, v156, v8
	ds_bpermute_b32 v135, v156, v9
	v_pk_mul_f32 v[182:183], v[12:13], v[182:183]
	v_pk_mul_f32 v[128:129], v[146:147], v[128:129]
	s_waitcnt lgkmcnt(3)
	v_mul_f32_e32 v221, v146, v131
	v_mov_b32_e32 v192, v15
	v_mov_b32_e32 v220, v185
	v_pk_fma_f32 v[128:129], v[190:191], v[128:129], v[182:183]
	s_waitcnt lgkmcnt(2)
	v_mul_f32_e32 v183, v146, v132
	v_mov_b32_e32 v188, v11
	v_mov_b32_e32 v182, v133
	v_pk_mul_f32 v[192:193], v[192:193], v[220:221]
	v_pk_mul_f32 v[132:133], v[188:189], v[182:183]
	s_waitcnt lgkmcnt(0)
	v_pk_mul_f32 v[134:135], v[146:147], v[134:135]
	v_mov_b32_e32 v131, v192
	v_mov_b32_e32 v185, v193
	v_mov_b32_e32 v197, v132
	v_mov_b32_e32 v219, v133
	v_pk_add_f32 v[130:131], v[130:131], v[184:185]
	v_pk_fma_f32 v[132:133], v[186:187], v[134:135], v[194:195]
	v_pk_add_f32 v[134:135], v[196:197], v[218:219]
;     DEVI void operator()(const f32x4 (&acc)[2][2][4][2], const Unit& u, int wr, int wc, int fr, int fq) const {
;     ...
;                         f32x4 v0 = acc[ai][bj][m][0], v1 = acc[ai][bj][m][1];
;                         if (rope) {
;                             const f32x4 c0 = *(const f32x4*)(cosT + (size_t)row * 16 + 8 * (fq & 1)), c1 = *(const f32x4*)(cosT + (size_t)row * 16 + 8 * (fq & 1) + 4);
;                             const f32x4 s0 = *(const f32x4*)(sinT + (size_t)row * 16 + 8 * (fq & 1)), s1 = *(const f32x4*)(sinT + (size_t)row * 16 + 8 * (fq & 1) + 4);
;                             const float sgn = (fq < 2) ? -1.0f : 1.0f;
; #pragma unroll
;                             for (int j = 0; j < 4; ++j) {
;                                 const float p0 = __shfl_xor(v0[j], 32), p1 = __shfl_xor(v1[j], 32);
;                                 v0[j] = v0[j] * c0[j] + sgn * p0 * s0[j];
;                                 v1[j] = v1[j] * c1[j] + sgn * p1 * s1[j];
;                             }
;                         }
;                         v0 *= sc; v1 *= sc;
;                         bf16_t* dst = P2 + (size_t)(arr0 + bj) * ((size_t)S * 128) + (size_t)row * 128 + cl;
;                         u32x4 w; w.x = cvt_pk_bf16(v0[0], v0[1]); w.y = cvt_pk_bf16(v0[2], v0[3]); w.z = cvt_pk_bf16(v1[0], v1[1]); w.w = cvt_pk_bf16(v1[2], v1[3]);
;                         *(u32x4*)dst = w;
;                     }
.LBB0_253:
	v_lshlrev_b64 v[178:179], 8, v[178:179]
	v_pk_mul_f32 v[130:131], v[174:175], v[130:131]
	v_pk_mul_f32 v[128:129], v[170:171], v[128:129]
	v_pk_mul_f32 v[134:135], v[174:175], v[134:135]
	v_pk_mul_f32 v[132:133], v[170:171], v[132:133]
	v_lshl_add_u64 v[174:175], s[24:25], 0, v[178:179]
	v_lshl_add_u64 v[174:175], v[174:175], 0, v[148:149]
	v_cvt_pk_bf16_f32 v128, v128, v129
	v_cvt_pk_bf16_f32 v129, v130, v131
	v_cvt_pk_bf16_f32 v130, v132, v133
	v_cvt_pk_bf16_f32 v131, v134, v135
	global_store_dwordx4 v[174:175], v[128:131], off sc1
	v_mov_b64_e32 v[134:135], v[2:3]
	s_and_b64 vcc, exec, s[8:9]
	v_mov_b64_e32 v[130:131], v[6:7]
	v_mov_b64_e32 v[128:129], v[4:5]
	v_mov_b64_e32 v[132:133], v[0:1]
	s_cbranch_vccnz .LBB0_255
	global_load_dwordx4 v[130:133], v[176:177], off offset:16
	s_nop 0
	global_load_dwordx4 v[174:177], v[176:177], off
	s_nop 0
	global_load_dwordx4 v[182:185], v[172:173], off offset:16
	global_load_dwordx4 v[186:189], v[172:173], off
	v_cmp_lt_i32_e32 vcc, v209, v203
	s_waitcnt vmcnt(0)
	v_mul_f32_e32 v190, v2, v132
	v_cndmask_b32_e32 v128, v202, v209, vcc
	v_lshlrev_b32_e32 v156, 2, v128
	v_pk_mul_f32 v[172:173], v[4:5], v[174:175]
	v_pk_mul_f32 v[174:175], v[0:1], v[130:131]
	ds_bpermute_b32 v131, v156, v6
	ds_bpermute_b32 v157, v156, v2
	ds_bpermute_b32 v128, v156, v4
	ds_bpermute_b32 v129, v156, v5
	v_mul_f32_e32 v130, v6, v176
	s_waitcnt lgkmcnt(0)
	v_mul_f32_e32 v131, v146, v131
	v_mul_f32_e32 v176, v188, v131
	v_mul_f32_e32 v131, v146, v157
	v_mul_f32_e32 v192, v184, v131
	ds_bpermute_b32 v131, v156, v7
	ds_bpermute_b32 v132, v156, v3
	ds_bpermute_b32 v134, v156, v0
	ds_bpermute_b32 v135, v156, v1
	v_pk_mul_f32 v[128:129], v[146:147], v[128:129]
	s_waitcnt lgkmcnt(3)
	v_mul_f32_e32 v195, v146, v131
	v_mov_b32_e32 v188, v7
	v_mov_b32_e32 v194, v177
	v_pk_fma_f32 v[128:129], v[186:187], v[128:129], v[172:173]
	s_waitcnt lgkmcnt(2)
	v_mul_f32_e32 v173, v146, v132
	v_mov_b32_e32 v184, v3
	v_mov_b32_e32 v172, v133
	v_pk_mul_f32 v[188:189], v[188:189], v[194:195]
	v_pk_mul_f32 v[132:133], v[184:185], v[172:173]
	s_waitcnt lgkmcnt(0)
	v_pk_mul_f32 v[134:135], v[146:147], v[134:135]
	v_mov_b32_e32 v131, v188
	v_mov_b32_e32 v177, v189
	v_mov_b32_e32 v191, v132
	v_mov_b32_e32 v193, v133
	v_pk_add_f32 v[130:131], v[130:131], v[176:177]
	v_pk_fma_f32 v[132:133], v[182:183], v[134:135], v[174:175]
	v_pk_add_f32 v[134:135], v[190:191], v[192:193]
.LBB0_255:
	v_mov_b32_e32 v172, v170
	v_mov_b32_e32 v173, v170
	v_pk_mul_f32 v[130:131], v[172:173], v[130:131]
	v_pk_mul_f32 v[128:129], v[170:171], v[128:129]
	v_pk_mul_f32 v[134:135], v[172:173], v[134:135]
	v_pk_mul_f32 v[132:133], v[170:171], v[132:133]
	v_lshl_add_u64 v[170:171], s[26:27], 0, v[178:179]
	v_lshl_add_u64 v[170:171], v[170:171], 0, v[148:149]
	v_cvt_pk_bf16_f32 v128, v128, v129
	v_cvt_pk_bf16_f32 v129, v130, v131
	v_cvt_pk_bf16_f32 v130, v132, v133
	v_cvt_pk_bf16_f32 v131, v134, v135
	global_store_dwordx4 v[170:171], v[128:131], off sc1
	s_mov_b64 s[0:1], 0

; DEVI float sigmoidf_(float x) { return __builtin_amdgcn_rcpf(1.0f + __expf(-x)); }
;     DEVI void operator()(const f32x4 (&acc)[2][2][4][2], const Unit& u, int wr, int wc, int fr, int fq) const {
;     ...
; #pragma unroll
;             for (int ai = 0; ai < 2; ++ai)
; #pragma unroll
;                 for (int m = 0; m < 4; ++m) {
;                     bf16_t* rowp = base + (size_t)(row0 + ai * 128 + m * 16) * ld + pnl * 256 + cl;
; #pragma unroll
;                     for (int bj = 0; bj < 2; ++bj) {
;                         f32x4 v0 = acc[ai][bj][m][0], v1 = acc[ai][bj][m][1];
;                         if (sg) {
; #pragma unroll
;                             for (int j = 0; j < 4; ++j) { v0[j] = sigmoidf_(v0[j]); v1[j] = sigmoidf_(v1[j]); }
;                         }
;                         u32x4 w; w.x = cvt_pk_bf16(v0[0], v0[1]); w.y = cvt_pk_bf16(v0[2], v0[3]); w.z = cvt_pk_bf16(v1[0], v1[1]); w.w = cvt_pk_bf16(v1[2], v1[3]);
;                         *(u32x4*)(rowp + bj * 128) = w;
;                     }
;                     __builtin_amdgcn_sched_barrier(0);
.LBB0_265:
	s_lshl_b32 s2, s43, 8
	s_ashr_i32 s3, s2, 31
	s_lshl_b64 s[2:3], s[2:3], 1
	s_add_u32 s0, s0, s2
	s_addc_u32 s1, s1, s3
	v_lshlrev_b32_e32 v148, 1, v144
	v_lshl_add_u64 v[128:129], s[0:1], 0, v[148:149]
	v_mad_i64_i32 v[130:131], s[0:1], s24, v168, 0
	v_lshl_add_u64 v[130:131], v[130:131], 1, v[128:129]
	v_cvt_pk_bf16_f32 v120, v120, v121
	v_cvt_pk_bf16_f32 v121, v122, v123
	v_cvt_pk_bf16_f32 v122, v124, v125
	v_cvt_pk_bf16_f32 v123, v126, v127
	s_and_b64 vcc, exec, s[8:9]
	global_store_dwordx4 v[130:131], v[120:123], off sc1
	s_cbranch_vccnz .LBB0_267
	v_mul_f32_e32 v116, 0xbfb8aa3b, v116
	v_mul_f32_e32 v112, 0xbfb8aa3b, v112
	v_mul_f32_e32 v117, 0xbfb8aa3b, v117
	v_mul_f32_e32 v113, 0xbfb8aa3b, v113
	v_mul_f32_e32 v118, 0xbfb8aa3b, v118
	v_mul_f32_e32 v114, 0xbfb8aa3b, v114
	v_mul_f32_e32 v119, 0xbfb8aa3b, v119
	v_mul_f32_e32 v115, 0xbfb8aa3b, v115
	v_exp_f32_e32 v116, v116
	v_exp_f32_e32 v112, v112
	v_exp_f32_e32 v117, v117
	v_exp_f32_e32 v113, v113
	v_exp_f32_e32 v118, v118
	v_exp_f32_e32 v114, v114
	v_exp_f32_e32 v119, v119
	v_exp_f32_e32 v115, v115
	v_add_f32_e32 v116, 1.0, v116
	v_add_f32_e32 v112, 1.0, v112
	v_add_f32_e32 v117, 1.0, v117
	v_add_f32_e32 v113, 1.0, v113
	v_add_f32_e32 v118, 1.0, v118
	v_add_f32_e32 v114, 1.0, v114
	v_add_f32_e32 v119, 1.0, v119
	v_add_f32_e32 v115, 1.0, v115
	v_rcp_f32_e32 v116, v116
	v_rcp_f32_e32 v112, v112
	v_rcp_f32_e32 v117, v117
	v_rcp_f32_e32 v113, v113
	v_rcp_f32_e32 v118, v118
	v_rcp_f32_e32 v114, v114
	v_rcp_f32_e32 v119, v119
	v_rcp_f32_e32 v115, v115
.LBB0_267:
	v_cvt_pk_bf16_f32 v116, v116, v117
	v_cvt_pk_bf16_f32 v117, v118, v119
	v_cvt_pk_bf16_f32 v118, v112, v113
	v_cvt_pk_bf16_f32 v119, v114, v115
	global_store_dwordx4 v[130:131], v[116:119], off offset:256 sc1
	s_and_b64 vcc, exec, s[8:9]
	s_cbranch_vccnz .LBB0_269
	v_mul_f32_e32 v108, 0xbfb8aa3b, v108
	v_mul_f32_e32 v104, 0xbfb8aa3b, v104
	v_mul_f32_e32 v109, 0xbfb8aa3b, v109
	v_mul_f32_e32 v105, 0xbfb8aa3b, v105
	v_mul_f32_e32 v110, 0xbfb8aa3b, v110
	v_mul_f32_e32 v106, 0xbfb8aa3b, v106
	v_mul_f32_e32 v111, 0xbfb8aa3b, v111
	v_mul_f32_e32 v107, 0xbfb8aa3b, v107
	v_exp_f32_e32 v108, v108
	v_exp_f32_e32 v104, v104
	v_exp_f32_e32 v109, v109
	v_exp_f32_e32 v105, v105
	v_exp_f32_e32 v110, v110
	v_exp_f32_e32 v106, v106
	v_exp_f32_e32 v111, v111
	v_exp_f32_e32 v107, v107
	v_add_f32_e32 v108, 1.0, v108
	v_add_f32_e32 v104, 1.0, v104
	v_add_f32_e32 v109, 1.0, v109
	v_add_f32_e32 v105, 1.0, v105
	v_add_f32_e32 v110, 1.0, v110
	v_add_f32_e32 v106, 1.0, v106
	v_add_f32_e32 v111, 1.0, v111
	v_add_f32_e32 v107, 1.0, v107
	v_rcp_f32_e32 v108, v108
	v_rcp_f32_e32 v104, v104
	v_rcp_f32_e32 v109, v109
	v_rcp_f32_e32 v105, v105
	v_rcp_f32_e32 v110, v110
	v_rcp_f32_e32 v106, v106
	v_rcp_f32_e32 v111, v111
	v_rcp_f32_e32 v107, v107
.LBB0_269:
	v_or_b32_e32 v112, 16, v168
	v_mad_i64_i32 v[112:113], s[0:1], s24, v112, 0
	v_lshl_add_u64 v[112:113], v[112:113], 1, v[128:129]
	v_cvt_pk_bf16_f32 v108, v108, v109
	v_cvt_pk_bf16_f32 v109, v110, v111
	v_cvt_pk_bf16_f32 v110, v104, v105
	v_cvt_pk_bf16_f32 v111, v106, v107
	s_and_b64 vcc, exec, s[8:9]
	global_store_dwordx4 v[112:113], v[108:111], off sc1
	s_cbranch_vccnz .LBB0_271
	v_mul_f32_e32 v100, 0xbfb8aa3b, v100
	v_mul_f32_e32 v96, 0xbfb8aa3b, v96
	v_mul_f32_e32 v101, 0xbfb8aa3b, v101
	v_mul_f32_e32 v97, 0xbfb8aa3b, v97
	v_mul_f32_e32 v102, 0xbfb8aa3b, v102
	v_mul_f32_e32 v98, 0xbfb8aa3b, v98
	v_mul_f32_e32 v103, 0xbfb8aa3b, v103
	v_mul_f32_e32 v99, 0xbfb8aa3b, v99
	v_exp_f32_e32 v100, v100
	v_exp_f32_e32 v96, v96
	v_exp_f32_e32 v101, v101
	v_exp_f32_e32 v97, v97
	v_exp_f32_e32 v102, v102
	v_exp_f32_e32 v98, v98
	v_exp_f32_e32 v103, v103
	v_exp_f32_e32 v99, v99
	v_add_f32_e32 v100, 1.0, v100
	v_add_f32_e32 v96, 1.0, v96
	v_add_f32_e32 v101, 1.0, v101
	v_add_f32_e32 v97, 1.0, v97
	v_add_f32_e32 v102, 1.0, v102
	v_add_f32_e32 v98, 1.0, v98
	v_add_f32_e32 v103, 1.0, v103
	v_add_f32_e32 v99, 1.0, v99
	v_rcp_f32_e32 v100, v100
	v_rcp_f32_e32 v96, v96
	v_rcp_f32_e32 v101, v101
	v_rcp_f32_e32 v97, v97
	v_rcp_f32_e32 v102, v102
	v_rcp_f32_e32 v98, v98
	v_rcp_f32_e32 v103, v103
	v_rcp_f32_e32 v99, v99
.LBB0_271:
	v_cvt_pk_bf16_f32 v100, v100, v101
	v_cvt_pk_bf16_f32 v101, v102, v103
	v_cvt_pk_bf16_f32 v102, v96, v97
	v_cvt_pk_bf16_f32 v103, v98, v99
	global_store_dwordx4 v[112:113], v[100:103], off offset:256 sc1
	s_and_b64 vcc, exec, s[8:9]
	s_cbranch_vccnz .LBB0_273
	v_mul_f32_e32 v92, 0xbfb8aa3b, v92
	v_mul_f32_e32 v88, 0xbfb8aa3b, v88
	v_mul_f32_e32 v93, 0xbfb8aa3b, v93
	v_mul_f32_e32 v89, 0xbfb8aa3b, v89
	v_mul_f32_e32 v94, 0xbfb8aa3b, v94
	v_mul_f32_e32 v90, 0xbfb8aa3b, v90
	v_mul_f32_e32 v95, 0xbfb8aa3b, v95
	v_mul_f32_e32 v91, 0xbfb8aa3b, v91
	v_exp_f32_e32 v92, v92
	v_exp_f32_e32 v88, v88
	v_exp_f32_e32 v93, v93
	v_exp_f32_e32 v89, v89
	v_exp_f32_e32 v94, v94
	v_exp_f32_e32 v90, v90
	v_exp_f32_e32 v95, v95
	v_exp_f32_e32 v91, v91
	v_add_f32_e32 v92, 1.0, v92
	v_add_f32_e32 v88, 1.0, v88
	v_add_f32_e32 v93, 1.0, v93
	v_add_f32_e32 v89, 1.0, v89
	v_add_f32_e32 v94, 1.0, v94
	v_add_f32_e32 v90, 1.0, v90
	v_add_f32_e32 v95, 1.0, v95
	v_add_f32_e32 v91, 1.0, v91
	v_rcp_f32_e32 v92, v92
	v_rcp_f32_e32 v88, v88
	v_rcp_f32_e32 v93, v93
	v_rcp_f32_e32 v89, v89
	v_rcp_f32_e32 v94, v94
	v_rcp_f32_e32 v90, v90
	v_rcp_f32_e32 v95, v95
	v_rcp_f32_e32 v91, v91
; DEVI float sigmoidf_(float x) { return __builtin_amdgcn_rcpf(1.0f + __expf(-x)); }
;     DEVI void operator()(const f32x4 (&acc)[2][2][4][2], const Unit& u, int wr, int wc, int fr, int fq) const {
;     ...
; #pragma unroll
;             for (int ai = 0; ai < 2; ++ai)
; #pragma unroll
;                 for (int m = 0; m < 4; ++m) {
;                     bf16_t* rowp = base + (size_t)(row0 + ai * 128 + m * 16) * ld + pnl * 256 + cl;
; #pragma unroll
;                     for (int bj = 0; bj < 2; ++bj) {
;                         f32x4 v0 = acc[ai][bj][m][0], v1 = acc[ai][bj][m][1];
;                         if (sg) {
; #pragma unroll
;                             for (int j = 0; j < 4; ++j) { v0[j] = sigmoidf_(v0[j]); v1[j] = sigmoidf_(v1[j]); }
;                         }
;                         u32x4 w; w.x = cvt_pk_bf16(v0[0], v0[1]); w.y = cvt_pk_bf16(v0[2], v0[3]); w.z = cvt_pk_bf16(v1[0], v1[1]); w.w = cvt_pk_bf16(v1[2], v1[3]);
;                         *(u32x4*)(rowp + bj * 128) = w;
;                     }
;                     __builtin_amdgcn_sched_barrier(0);
.LBB0_273:
	v_or_b32_e32 v96, 32, v168
	v_mad_i64_i32 v[96:97], s[0:1], s24, v96, 0
	v_lshl_add_u64 v[96:97], v[96:97], 1, v[128:129]
	v_cvt_pk_bf16_f32 v92, v92, v93
	v_cvt_pk_bf16_f32 v93, v94, v95
	v_cvt_pk_bf16_f32 v94, v88, v89
	v_cvt_pk_bf16_f32 v95, v90, v91
	s_and_b64 vcc, exec, s[8:9]
	global_store_dwordx4 v[96:97], v[92:95], off sc1
	s_cbranch_vccnz .LBB0_275
	v_mul_f32_e32 v84, 0xbfb8aa3b, v84
	v_mul_f32_e32 v80, 0xbfb8aa3b, v80
	v_mul_f32_e32 v85, 0xbfb8aa3b, v85
	v_mul_f32_e32 v81, 0xbfb8aa3b, v81
	v_mul_f32_e32 v86, 0xbfb8aa3b, v86
	v_mul_f32_e32 v82, 0xbfb8aa3b, v82
	v_mul_f32_e32 v87, 0xbfb8aa3b, v87
	v_mul_f32_e32 v83, 0xbfb8aa3b, v83
	v_exp_f32_e32 v84, v84
	v_exp_f32_e32 v80, v80
	v_exp_f32_e32 v85, v85
	v_exp_f32_e32 v81, v81
	v_exp_f32_e32 v86, v86
	v_exp_f32_e32 v82, v82
	v_exp_f32_e32 v87, v87
	v_exp_f32_e32 v83, v83
	v_add_f32_e32 v84, 1.0, v84
	v_add_f32_e32 v80, 1.0, v80
	v_add_f32_e32 v85, 1.0, v85
	v_add_f32_e32 v81, 1.0, v81
	v_add_f32_e32 v86, 1.0, v86
	v_add_f32_e32 v82, 1.0, v82
	v_add_f32_e32 v87, 1.0, v87
	v_add_f32_e32 v83, 1.0, v83
	v_rcp_f32_e32 v84, v84
	v_rcp_f32_e32 v80, v80
	v_rcp_f32_e32 v85, v85
	v_rcp_f32_e32 v81, v81
	v_rcp_f32_e32 v86, v86
	v_rcp_f32_e32 v82, v82
	v_rcp_f32_e32 v87, v87
	v_rcp_f32_e32 v83, v83
.LBB0_275:
	v_cvt_pk_bf16_f32 v84, v84, v85
	v_cvt_pk_bf16_f32 v85, v86, v87
	v_cvt_pk_bf16_f32 v86, v80, v81
	v_cvt_pk_bf16_f32 v87, v82, v83
	global_store_dwordx4 v[96:97], v[84:87], off offset:256 sc1
	s_and_b64 vcc, exec, s[8:9]
	s_cbranch_vccnz .LBB0_277
	v_mul_f32_e32 v76, 0xbfb8aa3b, v76
	v_mul_f32_e32 v72, 0xbfb8aa3b, v72
	v_mul_f32_e32 v77, 0xbfb8aa3b, v77
	v_mul_f32_e32 v73, 0xbfb8aa3b, v73
	v_mul_f32_e32 v78, 0xbfb8aa3b, v78
	v_mul_f32_e32 v74, 0xbfb8aa3b, v74
	v_mul_f32_e32 v79, 0xbfb8aa3b, v79
	v_mul_f32_e32 v75, 0xbfb8aa3b, v75
	v_exp_f32_e32 v76, v76
	v_exp_f32_e32 v72, v72
	v_exp_f32_e32 v77, v77
	v_exp_f32_e32 v73, v73
	v_exp_f32_e32 v78, v78
	v_exp_f32_e32 v74, v74
	v_exp_f32_e32 v79, v79
	v_exp_f32_e32 v75, v75
	v_add_f32_e32 v76, 1.0, v76
	v_add_f32_e32 v72, 1.0, v72
	v_add_f32_e32 v77, 1.0, v77
	v_add_f32_e32 v73, 1.0, v73
	v_add_f32_e32 v78, 1.0, v78
	v_add_f32_e32 v74, 1.0, v74
	v_add_f32_e32 v79, 1.0, v79
	v_add_f32_e32 v75, 1.0, v75
	v_rcp_f32_e32 v76, v76
	v_rcp_f32_e32 v72, v72
	v_rcp_f32_e32 v77, v77
	v_rcp_f32_e32 v73, v73
	v_rcp_f32_e32 v78, v78
	v_rcp_f32_e32 v74, v74
	v_rcp_f32_e32 v79, v79
	v_rcp_f32_e32 v75, v75
.LBB0_277:
	v_or_b32_e32 v80, 48, v168
	v_mad_i64_i32 v[80:81], s[0:1], s24, v80, 0
	v_lshl_add_u64 v[80:81], v[80:81], 1, v[128:129]
	v_cvt_pk_bf16_f32 v76, v76, v77
	v_cvt_pk_bf16_f32 v77, v78, v79
	v_cvt_pk_bf16_f32 v78, v72, v73
	v_cvt_pk_bf16_f32 v79, v74, v75
	s_and_b64 vcc, exec, s[8:9]
	global_store_dwordx4 v[80:81], v[76:79], off sc1
	s_cbranch_vccnz .LBB0_279
	v_mul_f32_e32 v68, 0xbfb8aa3b, v68
	v_mul_f32_e32 v64, 0xbfb8aa3b, v64
	v_mul_f32_e32 v69, 0xbfb8aa3b, v69
	v_mul_f32_e32 v65, 0xbfb8aa3b, v65
	v_mul_f32_e32 v70, 0xbfb8aa3b, v70
	v_mul_f32_e32 v66, 0xbfb8aa3b, v66
	v_mul_f32_e32 v71, 0xbfb8aa3b, v71
	v_mul_f32_e32 v67, 0xbfb8aa3b, v67
	v_exp_f32_e32 v68, v68
	v_exp_f32_e32 v64, v64
	v_exp_f32_e32 v69, v69
	v_exp_f32_e32 v65, v65
	v_exp_f32_e32 v70, v70
	v_exp_f32_e32 v66, v66
	v_exp_f32_e32 v71, v71
	v_exp_f32_e32 v67, v67
	v_add_f32_e32 v68, 1.0, v68
	v_add_f32_e32 v64, 1.0, v64
	v_add_f32_e32 v69, 1.0, v69
	v_add_f32_e32 v65, 1.0, v65
	v_add_f32_e32 v70, 1.0, v70
	v_add_f32_e32 v66, 1.0, v66
	v_add_f32_e32 v71, 1.0, v71
	v_add_f32_e32 v67, 1.0, v67
	v_rcp_f32_e32 v68, v68
	v_rcp_f32_e32 v64, v64
	v_rcp_f32_e32 v69, v69
	v_rcp_f32_e32 v65, v65
	v_rcp_f32_e32 v70, v70
	v_rcp_f32_e32 v66, v66
	v_rcp_f32_e32 v71, v71
	v_rcp_f32_e32 v67, v67
.LBB0_279:
	v_cvt_pk_bf16_f32 v68, v68, v69
	v_cvt_pk_bf16_f32 v69, v70, v71
	v_cvt_pk_bf16_f32 v70, v64, v65
	v_cvt_pk_bf16_f32 v71, v66, v67
	global_store_dwordx4 v[80:81], v[68:71], off offset:256 sc1
	s_and_b64 vcc, exec, s[8:9]
	s_cbranch_vccnz .LBB0_281
	v_mul_f32_e32 v60, 0xbfb8aa3b, v60
	v_mul_f32_e32 v56, 0xbfb8aa3b, v56
	v_mul_f32_e32 v61, 0xbfb8aa3b, v61
	v_mul_f32_e32 v57, 0xbfb8aa3b, v57
	v_mul_f32_e32 v62, 0xbfb8aa3b, v62
	v_mul_f32_e32 v58, 0xbfb8aa3b, v58
	v_mul_f32_e32 v63, 0xbfb8aa3b, v63
	v_mul_f32_e32 v59, 0xbfb8aa3b, v59
	v_exp_f32_e32 v60, v60
	v_exp_f32_e32 v56, v56
	v_exp_f32_e32 v61, v61
	v_exp_f32_e32 v57, v57
	v_exp_f32_e32 v62, v62
	v_exp_f32_e32 v58, v58
	v_exp_f32_e32 v63, v63
	v_exp_f32_e32 v59, v59
	v_add_f32_e32 v60, 1.0, v60
	v_add_f32_e32 v56, 1.0, v56
	v_add_f32_e32 v61, 1.0, v61
	v_add_f32_e32 v57, 1.0, v57
	v_add_f32_e32 v62, 1.0, v62
	v_add_f32_e32 v58, 1.0, v58
	v_add_f32_e32 v63, 1.0, v63
	v_add_f32_e32 v59, 1.0, v59
	v_rcp_f32_e32 v60, v60
	v_rcp_f32_e32 v56, v56
	v_rcp_f32_e32 v61, v61
	v_rcp_f32_e32 v57, v57
	v_rcp_f32_e32 v62, v62
	v_rcp_f32_e32 v58, v58
	v_rcp_f32_e32 v63, v63
	v_rcp_f32_e32 v59, v59
.LBB0_281:
	v_add_u32_e32 v64, 0x80, v168
	v_mad_i64_i32 v[64:65], s[0:1], s24, v64, 0
	v_lshl_add_u64 v[64:65], v[64:65], 1, v[128:129]
	v_cvt_pk_bf16_f32 v60, v60, v61
	v_cvt_pk_bf16_f32 v61, v62, v63
	v_cvt_pk_bf16_f32 v62, v56, v57
	v_cvt_pk_bf16_f32 v63, v58, v59
	s_and_b64 vcc, exec, s[8:9]
	global_store_dwordx4 v[64:65], v[60:63], off sc1
	s_cbranch_vccnz .LBB0_283
	v_mul_f32_e32 v52, 0xbfb8aa3b, v52
	v_mul_f32_e32 v48, 0xbfb8aa3b, v48
	v_mul_f32_e32 v53, 0xbfb8aa3b, v53
	v_mul_f32_e32 v49, 0xbfb8aa3b, v49
	v_mul_f32_e32 v54, 0xbfb8aa3b, v54
	v_mul_f32_e32 v50, 0xbfb8aa3b, v50
	v_mul_f32_e32 v55, 0xbfb8aa3b, v55
	v_mul_f32_e32 v51, 0xbfb8aa3b, v51
	v_exp_f32_e32 v52, v52
	v_exp_f32_e32 v48, v48
	v_exp_f32_e32 v53, v53
	v_exp_f32_e32 v49, v49
	v_exp_f32_e32 v54, v54
	v_exp_f32_e32 v50, v50
	v_exp_f32_e32 v55, v55
	v_exp_f32_e32 v51, v51
	v_add_f32_e32 v52, 1.0, v52
	v_add_f32_e32 v48, 1.0, v48
	v_add_f32_e32 v53, 1.0, v53
	v_add_f32_e32 v49, 1.0, v49
	v_add_f32_e32 v54, 1.0, v54
	v_add_f32_e32 v50, 1.0, v50
	v_add_f32_e32 v55, 1.0, v55
	v_add_f32_e32 v51, 1.0, v51
	v_rcp_f32_e32 v52, v52
	v_rcp_f32_e32 v48, v48
	v_rcp_f32_e32 v53, v53
	v_rcp_f32_e32 v49, v49
	v_rcp_f32_e32 v54, v54
	v_rcp_f32_e32 v50, v50
	v_rcp_f32_e32 v55, v55
	v_rcp_f32_e32 v51, v51
; DEVI float sigmoidf_(float x) { return __builtin_amdgcn_rcpf(1.0f + __expf(-x)); }
;     DEVI void operator()(const f32x4 (&acc)[2][2][4][2], const Unit& u, int wr, int wc, int fr, int fq) const {
;     ...
; #pragma unroll
;             for (int ai = 0; ai < 2; ++ai)
; #pragma unroll
;                 for (int m = 0; m < 4; ++m) {
;                     bf16_t* rowp = base + (size_t)(row0 + ai * 128 + m * 16) * ld + pnl * 256 + cl;
; #pragma unroll
;                     for (int bj = 0; bj < 2; ++bj) {
;                         f32x4 v0 = acc[ai][bj][m][0], v1 = acc[ai][bj][m][1];
;                         if (sg) {
; #pragma unroll
;                             for (int j = 0; j < 4; ++j) { v0[j] = sigmoidf_(v0[j]); v1[j] = sigmoidf_(v1[j]); }
;                         }
;                         u32x4 w; w.x = cvt_pk_bf16(v0[0], v0[1]); w.y = cvt_pk_bf16(v0[2], v0[3]); w.z = cvt_pk_bf16(v1[0], v1[1]); w.w = cvt_pk_bf16(v1[2], v1[3]);
;                         *(u32x4*)(rowp + bj * 128) = w;
;                     }
;                     __builtin_amdgcn_sched_barrier(0);
.LBB0_283:
	v_cvt_pk_bf16_f32 v52, v52, v53
	v_cvt_pk_bf16_f32 v53, v54, v55
	v_cvt_pk_bf16_f32 v54, v48, v49
	v_cvt_pk_bf16_f32 v55, v50, v51
	global_store_dwordx4 v[64:65], v[52:55], off offset:256 sc1
	s_and_b64 vcc, exec, s[8:9]
	s_cbranch_vccnz .LBB0_285
	v_mul_f32_e32 v44, 0xbfb8aa3b, v44
	v_mul_f32_e32 v40, 0xbfb8aa3b, v40
	v_mul_f32_e32 v45, 0xbfb8aa3b, v45
	v_mul_f32_e32 v41, 0xbfb8aa3b, v41
	v_mul_f32_e32 v46, 0xbfb8aa3b, v46
	v_mul_f32_e32 v42, 0xbfb8aa3b, v42
	v_mul_f32_e32 v47, 0xbfb8aa3b, v47
	v_mul_f32_e32 v43, 0xbfb8aa3b, v43
	v_exp_f32_e32 v44, v44
	v_exp_f32_e32 v40, v40
	v_exp_f32_e32 v45, v45
	v_exp_f32_e32 v41, v41
	v_exp_f32_e32 v46, v46
	v_exp_f32_e32 v42, v42
	v_exp_f32_e32 v47, v47
	v_exp_f32_e32 v43, v43
	v_add_f32_e32 v44, 1.0, v44
	v_add_f32_e32 v40, 1.0, v40
	v_add_f32_e32 v45, 1.0, v45
	v_add_f32_e32 v41, 1.0, v41
	v_add_f32_e32 v46, 1.0, v46
	v_add_f32_e32 v42, 1.0, v42
	v_add_f32_e32 v47, 1.0, v47
	v_add_f32_e32 v43, 1.0, v43
	v_rcp_f32_e32 v44, v44
	v_rcp_f32_e32 v40, v40
	v_rcp_f32_e32 v45, v45
	v_rcp_f32_e32 v41, v41
	v_rcp_f32_e32 v46, v46
	v_rcp_f32_e32 v42, v42
	v_rcp_f32_e32 v47, v47
	v_rcp_f32_e32 v43, v43
.LBB0_285:
	v_add_u32_e32 v48, 0x90, v168
	v_mad_i64_i32 v[48:49], s[0:1], s24, v48, 0
	v_lshl_add_u64 v[48:49], v[48:49], 1, v[128:129]
	v_cvt_pk_bf16_f32 v44, v44, v45
	v_cvt_pk_bf16_f32 v45, v46, v47
	v_cvt_pk_bf16_f32 v46, v40, v41
	v_cvt_pk_bf16_f32 v47, v42, v43
	s_and_b64 vcc, exec, s[8:9]
	global_store_dwordx4 v[48:49], v[44:47], off sc1
	s_cbranch_vccnz .LBB0_287
	v_mul_f32_e32 v36, 0xbfb8aa3b, v36
	v_mul_f32_e32 v32, 0xbfb8aa3b, v32
	v_mul_f32_e32 v37, 0xbfb8aa3b, v37
	v_mul_f32_e32 v33, 0xbfb8aa3b, v33
	v_mul_f32_e32 v38, 0xbfb8aa3b, v38
	v_mul_f32_e32 v34, 0xbfb8aa3b, v34
	v_mul_f32_e32 v39, 0xbfb8aa3b, v39
	v_mul_f32_e32 v35, 0xbfb8aa3b, v35
	v_exp_f32_e32 v36, v36
	v_exp_f32_e32 v32, v32
	v_exp_f32_e32 v37, v37
	v_exp_f32_e32 v33, v33
	v_exp_f32_e32 v38, v38
	v_exp_f32_e32 v34, v34
	v_exp_f32_e32 v39, v39
	v_exp_f32_e32 v35, v35
	v_add_f32_e32 v36, 1.0, v36
	v_add_f32_e32 v32, 1.0, v32
	v_add_f32_e32 v37, 1.0, v37
	v_add_f32_e32 v33, 1.0, v33
	v_add_f32_e32 v38, 1.0, v38
	v_add_f32_e32 v34, 1.0, v34
	v_add_f32_e32 v39, 1.0, v39
	v_add_f32_e32 v35, 1.0, v35
	v_rcp_f32_e32 v36, v36
	v_rcp_f32_e32 v32, v32
	v_rcp_f32_e32 v37, v37
	v_rcp_f32_e32 v33, v33
	v_rcp_f32_e32 v38, v38
	v_rcp_f32_e32 v34, v34
	v_rcp_f32_e32 v39, v39
	v_rcp_f32_e32 v35, v35
.LBB0_287:
	v_cvt_pk_bf16_f32 v36, v36, v37
	v_cvt_pk_bf16_f32 v37, v38, v39
	v_cvt_pk_bf16_f32 v38, v32, v33
	v_cvt_pk_bf16_f32 v39, v34, v35
	global_store_dwordx4 v[48:49], v[36:39], off offset:256 sc1
	s_and_b64 vcc, exec, s[8:9]
	s_cbranch_vccnz .LBB0_289
	v_mul_f32_e32 v28, 0xbfb8aa3b, v28
	v_mul_f32_e32 v24, 0xbfb8aa3b, v24
	v_mul_f32_e32 v29, 0xbfb8aa3b, v29
	v_mul_f32_e32 v25, 0xbfb8aa3b, v25
	v_mul_f32_e32 v30, 0xbfb8aa3b, v30
	v_mul_f32_e32 v26, 0xbfb8aa3b, v26
	v_mul_f32_e32 v31, 0xbfb8aa3b, v31
	v_mul_f32_e32 v27, 0xbfb8aa3b, v27
	v_exp_f32_e32 v28, v28
	v_exp_f32_e32 v24, v24
	v_exp_f32_e32 v29, v29
	v_exp_f32_e32 v25, v25
	v_exp_f32_e32 v30, v30
	v_exp_f32_e32 v26, v26
	v_exp_f32_e32 v31, v31
	v_exp_f32_e32 v27, v27
	v_add_f32_e32 v28, 1.0, v28
	v_add_f32_e32 v24, 1.0, v24
	v_add_f32_e32 v29, 1.0, v29
	v_add_f32_e32 v25, 1.0, v25
	v_add_f32_e32 v30, 1.0, v30
	v_add_f32_e32 v26, 1.0, v26
	v_add_f32_e32 v31, 1.0, v31
	v_add_f32_e32 v27, 1.0, v27
	v_rcp_f32_e32 v28, v28
	v_rcp_f32_e32 v24, v24
	v_rcp_f32_e32 v29, v29
	v_rcp_f32_e32 v25, v25
	v_rcp_f32_e32 v30, v30
	v_rcp_f32_e32 v26, v26
	v_rcp_f32_e32 v31, v31
	v_rcp_f32_e32 v27, v27
; DEVI float sigmoidf_(float x) { return __builtin_amdgcn_rcpf(1.0f + __expf(-x)); }
;     DEVI void operator()(const f32x4 (&acc)[2][2][4][2], const Unit& u, int wr, int wc, int fr, int fq) const {
;     ...
; #pragma unroll
;             for (int ai = 0; ai < 2; ++ai)
; #pragma unroll
;                 for (int m = 0; m < 4; ++m) {
;                     bf16_t* rowp = base + (size_t)(row0 + ai * 128 + m * 16) * ld + pnl * 256 + cl;
; #pragma unroll
;                     for (int bj = 0; bj < 2; ++bj) {
;                         f32x4 v0 = acc[ai][bj][m][0], v1 = acc[ai][bj][m][1];
;                         if (sg) {
; #pragma unroll
;                             for (int j = 0; j < 4; ++j) { v0[j] = sigmoidf_(v0[j]); v1[j] = sigmoidf_(v1[j]); }
;                         }
;                         u32x4 w; w.x = cvt_pk_bf16(v0[0], v0[1]); w.y = cvt_pk_bf16(v0[2], v0[3]); w.z = cvt_pk_bf16(v1[0], v1[1]); w.w = cvt_pk_bf16(v1[2], v1[3]);
;                         *(u32x4*)(rowp + bj * 128) = w;
;                     }
;                     __builtin_amdgcn_sched_barrier(0);
.LBB0_289:
	v_add_u32_e32 v32, 0xa0, v168
	v_mad_i64_i32 v[32:33], s[0:1], s24, v32, 0
	v_lshl_add_u64 v[32:33], v[32:33], 1, v[128:129]
	v_cvt_pk_bf16_f32 v28, v28, v29
	v_cvt_pk_bf16_f32 v29, v30, v31
	v_cvt_pk_bf16_f32 v30, v24, v25
	v_cvt_pk_bf16_f32 v31, v26, v27
	s_and_b64 vcc, exec, s[8:9]
	global_store_dwordx4 v[32:33], v[28:31], off sc1
	s_cbranch_vccnz .LBB0_291
	v_mul_f32_e32 v20, 0xbfb8aa3b, v20
	v_mul_f32_e32 v16, 0xbfb8aa3b, v16
	v_mul_f32_e32 v21, 0xbfb8aa3b, v21
	v_mul_f32_e32 v17, 0xbfb8aa3b, v17
	v_mul_f32_e32 v22, 0xbfb8aa3b, v22
	v_mul_f32_e32 v18, 0xbfb8aa3b, v18
	v_mul_f32_e32 v23, 0xbfb8aa3b, v23
	v_mul_f32_e32 v19, 0xbfb8aa3b, v19
	v_exp_f32_e32 v20, v20
	v_exp_f32_e32 v16, v16
	v_exp_f32_e32 v21, v21
	v_exp_f32_e32 v17, v17
	v_exp_f32_e32 v22, v22
	v_exp_f32_e32 v18, v18
	v_exp_f32_e32 v23, v23
	v_exp_f32_e32 v19, v19
	v_add_f32_e32 v20, 1.0, v20
	v_add_f32_e32 v16, 1.0, v16
	v_add_f32_e32 v21, 1.0, v21
	v_add_f32_e32 v17, 1.0, v17
	v_add_f32_e32 v22, 1.0, v22
	v_add_f32_e32 v18, 1.0, v18
	v_add_f32_e32 v23, 1.0, v23
	v_add_f32_e32 v19, 1.0, v19
	v_rcp_f32_e32 v20, v20
	v_rcp_f32_e32 v16, v16
	v_rcp_f32_e32 v21, v21
	v_rcp_f32_e32 v17, v17
	v_rcp_f32_e32 v22, v22
	v_rcp_f32_e32 v18, v18
	v_rcp_f32_e32 v23, v23
	v_rcp_f32_e32 v19, v19
.LBB0_291:
	v_cvt_pk_bf16_f32 v20, v20, v21
	v_cvt_pk_bf16_f32 v21, v22, v23
	v_cvt_pk_bf16_f32 v22, v16, v17
	v_cvt_pk_bf16_f32 v23, v18, v19
	global_store_dwordx4 v[32:33], v[20:23], off offset:256 sc1
	s_and_b64 vcc, exec, s[8:9]
	s_cbranch_vccnz .LBB0_293
	v_mul_f32_e32 v12, 0xbfb8aa3b, v12
	v_mul_f32_e32 v8, 0xbfb8aa3b, v8
	v_mul_f32_e32 v13, 0xbfb8aa3b, v13
	v_mul_f32_e32 v9, 0xbfb8aa3b, v9
	v_mul_f32_e32 v14, 0xbfb8aa3b, v14
	v_mul_f32_e32 v10, 0xbfb8aa3b, v10
	v_mul_f32_e32 v15, 0xbfb8aa3b, v15
	v_mul_f32_e32 v11, 0xbfb8aa3b, v11
	v_exp_f32_e32 v12, v12
	v_exp_f32_e32 v8, v8
	v_exp_f32_e32 v13, v13
	v_exp_f32_e32 v9, v9
	v_exp_f32_e32 v14, v14
	v_exp_f32_e32 v10, v10
	v_exp_f32_e32 v15, v15
	v_exp_f32_e32 v11, v11
	v_add_f32_e32 v12, 1.0, v12
	v_add_f32_e32 v8, 1.0, v8
	v_add_f32_e32 v13, 1.0, v13
	v_add_f32_e32 v9, 1.0, v9
	v_add_f32_e32 v14, 1.0, v14
	v_add_f32_e32 v10, 1.0, v10
	v_add_f32_e32 v15, 1.0, v15
	v_add_f32_e32 v11, 1.0, v11
	v_rcp_f32_e32 v12, v12
	v_rcp_f32_e32 v8, v8
	v_rcp_f32_e32 v13, v13
	v_rcp_f32_e32 v9, v9
	v_rcp_f32_e32 v14, v14
	v_rcp_f32_e32 v10, v10
	v_rcp_f32_e32 v15, v15
	v_rcp_f32_e32 v11, v11
.LBB0_293:
	v_add_u32_e32 v16, 0xb0, v168
	v_mad_i64_i32 v[16:17], s[0:1], s24, v16, 0
	v_lshl_add_u64 v[16:17], v[16:17], 1, v[128:129]
	v_cvt_pk_bf16_f32 v12, v12, v13
	v_cvt_pk_bf16_f32 v13, v14, v15
	v_cvt_pk_bf16_f32 v14, v8, v9
	v_cvt_pk_bf16_f32 v15, v10, v11
	s_and_b64 vcc, exec, s[8:9]
	global_store_dwordx4 v[16:17], v[12:15], off sc1
	s_cbranch_vccnz .LBB0_207
	v_mul_f32_e32 v4, 0xbfb8aa3b, v4
	v_mul_f32_e32 v0, 0xbfb8aa3b, v0
	v_mul_f32_e32 v5, 0xbfb8aa3b, v5
	v_mul_f32_e32 v1, 0xbfb8aa3b, v1
	v_mul_f32_e32 v6, 0xbfb8aa3b, v6
	v_mul_f32_e32 v2, 0xbfb8aa3b, v2
	v_mul_f32_e32 v7, 0xbfb8aa3b, v7
	v_mul_f32_e32 v3, 0xbfb8aa3b, v3
	v_exp_f32_e32 v4, v4
	v_exp_f32_e32 v0, v0
	v_exp_f32_e32 v5, v5
	v_exp_f32_e32 v1, v1
	v_exp_f32_e32 v6, v6
	v_exp_f32_e32 v2, v2
	v_exp_f32_e32 v7, v7
	v_exp_f32_e32 v3, v3
	v_add_f32_e32 v4, 1.0, v4
	v_add_f32_e32 v0, 1.0, v0
	v_add_f32_e32 v5, 1.0, v5
	v_add_f32_e32 v1, 1.0, v1
	v_add_f32_e32 v6, 1.0, v6
	v_add_f32_e32 v2, 1.0, v2
	v_add_f32_e32 v7, 1.0, v7
	v_add_f32_e32 v3, 1.0, v3
	v_rcp_f32_e32 v4, v4
	v_rcp_f32_e32 v0, v0
	v_rcp_f32_e32 v5, v5
	v_rcp_f32_e32 v1, v1
	v_rcp_f32_e32 v6, v6
	v_rcp_f32_e32 v2, v2
	v_rcp_f32_e32 v7, v7
	v_rcp_f32_e32 v3, v3
	s_branch .LBB0_207
